# GEMM MMA blocks: one priority raise per 32-MFMA block (mid-block s_setprio 0/1 toggle removed)
# baseline (speedup 1.0000x reference)
.LBB0_565:
	s_ashr_i32 s25, s24, 31
	s_lshl_b64 s[26:27], s[24:25], 19
	s_add_u32 s26, s84, s26
	s_addc_u32 s27, s85, s27
	s_and_b64 s[28:29], s[10:11], exec
	s_cselect_b32 s3, s27, s1
	s_cselect_b32 s25, s26, s0
	s_ashr_i32 s23, s22, 31
	s_lshl_b64 s[28:29], s[22:23], 19
	s_add_u32 s28, s37, s28
	s_addc_u32 s29, s38, s29
	s_and_b64 s[34:35], s[10:11], exec
	s_cselect_b32 s23, s29, s31
	s_cselect_b32 s48, s28, s30
	s_add_u32 s0, s0, 0x40080
	s_addc_u32 s1, s1, 0
	s_add_u32 s49, s30, 0x100
	s_addc_u32 s50, s31, 0
	s_mov_b32 s51, -2
	s_waitcnt lgkmcnt(0)
	s_add_u32 s30, s0, 0xfffc0080
	s_addc_u32 s31, s1, -1
	s_add_i32 s52, 0, 0x10000
	s_cmp_eq_u32 s51, 12
	s_cselect_b32 s35, s3, s31
	s_cselect_b32 s34, s25, s30
	s_cselect_b32 s31, s23, s50
	s_cselect_b32 s30, s48, s49
	s_add_i32 s54, 0, 0x14000
	v_add_u32_e32 v158, s52, v199
	v_add_u32_e32 v174, s54, v199
	ds_read_b128 v[134:137], v158
	ds_read_b128 v[150:153], v158 offset:1024
	ds_read_b128 v[154:157], v158 offset:2048
	ds_read_b128 v[158:161], v158 offset:3072
	ds_read_b128 v[162:165], v174
	ds_read_b128 v[166:169], v174 offset:1024
	ds_read_b128 v[170:173], v174 offset:2048
	ds_read_b128 v[182:185], v174 offset:3072
	v_lshl_add_u64 v[174:175], s[0:1], 0, v[146:147]
	s_add_i32 m0, s39, 0xc000
	ds_read_b128 v[186:189], v201
	ds_read_b128 v[202:205], v201 offset:1024
	ds_read_b128 v[206:209], v201 offset:2048
	ds_read_b128 v[210:213], v201 offset:3072
	ds_read_b128 v[214:217], v201 offset:4096
	ds_read_b128 v[218:221], v201 offset:5120
	ds_read_b128 v[222:225], v201 offset:6144
	ds_read_b128 v[226:229], v201 offset:7168
	global_load_lds_dwordx4 v[174:175], off
	v_lshl_add_u64 v[174:175], s[0:1], 0, v[148:149]
	s_add_i32 m0, s39, 0xe000
	s_nop 0
	global_load_lds_dwordx4 v[174:175], off
	s_waitcnt vmcnt(8)
	s_waitcnt lgkmcnt(0)
	s_barrier
	s_setprio 1
	s_waitcnt lgkmcnt(0)
	v_mfma_f32_16x16x32_bf16 v[130:133], v[134:137], v[186:189], 0
	v_mfma_f32_16x16x32_bf16 v[130:133], v[150:153], v[202:205], v[130:133]
	v_mfma_f32_16x16x32_bf16 v[126:129], v[154:157], v[186:189], 0
	v_mfma_f32_16x16x32_bf16 v[126:129], v[158:161], v[202:205], v[126:129]
	v_mfma_f32_16x16x32_bf16 v[114:117], v[134:137], v[206:209], 0
	v_mfma_f32_16x16x32_bf16 v[114:117], v[150:153], v[210:213], v[114:117]
	v_mfma_f32_16x16x32_bf16 v[110:113], v[154:157], v[206:209], 0
	v_mfma_f32_16x16x32_bf16 v[110:113], v[158:161], v[210:213], v[110:113]
	v_mfma_f32_16x16x32_bf16 v[98:101], v[134:137], v[214:217], 0
	v_mfma_f32_16x16x32_bf16 v[98:101], v[150:153], v[218:221], v[98:101]
	v_mfma_f32_16x16x32_bf16 v[94:97], v[154:157], v[214:217], 0
	v_mfma_f32_16x16x32_bf16 v[94:97], v[158:161], v[218:221], v[94:97]
	v_mfma_f32_16x16x32_bf16 v[82:85], v[134:137], v[222:225], 0
	v_mfma_f32_16x16x32_bf16 v[82:85], v[150:153], v[226:229], v[82:85]
	v_mfma_f32_16x16x32_bf16 v[78:81], v[154:157], v[222:225], 0
	v_mfma_f32_16x16x32_bf16 v[78:81], v[158:161], v[226:229], v[78:81]
	v_mfma_f32_16x16x32_bf16 v[122:125], v[162:165], v[186:189], 0
	v_mfma_f32_16x16x32_bf16 v[122:125], v[166:169], v[202:205], v[122:125]
	v_mfma_f32_16x16x32_bf16 v[118:121], v[170:173], v[186:189], 0
	v_mfma_f32_16x16x32_bf16 v[118:121], v[182:185], v[202:205], v[118:121]
	v_mfma_f32_16x16x32_bf16 v[106:109], v[162:165], v[206:209], 0
	v_mfma_f32_16x16x32_bf16 v[106:109], v[166:169], v[210:213], v[106:109]
	v_mfma_f32_16x16x32_bf16 v[102:105], v[170:173], v[206:209], 0
	v_mfma_f32_16x16x32_bf16 v[102:105], v[182:185], v[210:213], v[102:105]
	v_mfma_f32_16x16x32_bf16 v[90:93], v[162:165], v[214:217], 0
	v_mfma_f32_16x16x32_bf16 v[90:93], v[166:169], v[218:221], v[90:93]
	v_mfma_f32_16x16x32_bf16 v[86:89], v[170:173], v[214:217], 0
	v_mfma_f32_16x16x32_bf16 v[86:89], v[182:185], v[218:221], v[86:89]
	v_mfma_f32_16x16x32_bf16 v[74:77], v[162:165], v[222:225], 0
	v_mfma_f32_16x16x32_bf16 v[74:77], v[166:169], v[226:229], v[74:77]
	v_mfma_f32_16x16x32_bf16 v[70:73], v[170:173], v[222:225], 0
	v_mfma_f32_16x16x32_bf16 v[70:73], v[182:185], v[226:229], v[70:73]
	s_setprio 0
	s_barrier
	s_add_i32 s52, s52, s36
	v_lshl_add_u64 v[174:175], s[30:31], 0, v[0:1]
	s_mov_b32 m0, s52
	ds_read_b128 v[186:189], v201 offset:16384
	ds_read_b128 v[202:205], v201 offset:17408
	ds_read_b128 v[206:209], v201 offset:18432
	ds_read_b128 v[210:213], v201 offset:19456
	ds_read_b128 v[214:217], v201 offset:20480
	ds_read_b128 v[218:221], v201 offset:21504
	ds_read_b128 v[222:225], v201 offset:22528
	ds_read_b128 v[226:229], v201 offset:23552
	global_load_lds_dwordx4 v[174:175], off
	s_add_i32 m0, s52, 0x2000
	s_add_u32 s52, s30, 0x40000
	v_lshl_add_u64 v[190:191], s[30:31], 0, v[14:15]
	s_addc_u32 s53, s31, 0
	s_add_i32 s54, s54, s36
	global_load_lds_dwordx4 v[190:191], off
	v_lshl_add_u64 v[230:231], s[52:53], 0, v[0:1]
	s_mov_b32 m0, s54
	v_lshl_add_u64 v[232:233], s[34:35], 0, v[138:139]
	global_load_lds_dwordx4 v[230:231], off
	v_lshl_add_u64 v[230:231], s[52:53], 0, v[14:15]
	s_add_i32 m0, s54, 0x2000
	s_nop 0
	global_load_lds_dwordx4 v[230:231], off
	v_lshl_add_u64 v[230:231], s[34:35], 0, v[140:141]
	s_mov_b32 m0, s39
	s_nop 0
	global_load_lds_dwordx4 v[230:231], off
	s_mov_b32 m0, s40
	s_nop 0
	global_load_lds_dwordx4 v[232:233], off
	s_waitcnt vmcnt(8)
	s_waitcnt lgkmcnt(0)
	s_barrier
	s_setprio 1
	s_waitcnt lgkmcnt(0)
	v_mfma_f32_16x16x32_bf16 v[66:69], v[134:137], v[186:189], 0
	v_mfma_f32_16x16x32_bf16 v[66:69], v[150:153], v[202:205], v[66:69]
	v_mfma_f32_16x16x32_bf16 v[62:65], v[154:157], v[186:189], 0
	v_mfma_f32_16x16x32_bf16 v[62:65], v[158:161], v[202:205], v[62:65]
	v_mfma_f32_16x16x32_bf16 v[50:53], v[134:137], v[206:209], 0
	v_mfma_f32_16x16x32_bf16 v[50:53], v[150:153], v[210:213], v[50:53]
	v_mfma_f32_16x16x32_bf16 v[46:49], v[154:157], v[206:209], 0
	v_mfma_f32_16x16x32_bf16 v[46:49], v[158:161], v[210:213], v[46:49]
	v_mfma_f32_16x16x32_bf16 v[34:37], v[134:137], v[214:217], 0
	v_mfma_f32_16x16x32_bf16 v[34:37], v[150:153], v[218:221], v[34:37]
	v_mfma_f32_16x16x32_bf16 v[30:33], v[154:157], v[214:217], 0
	v_mfma_f32_16x16x32_bf16 v[30:33], v[158:161], v[218:221], v[30:33]
	v_mfma_f32_16x16x32_bf16 v[18:21], v[134:137], v[222:225], 0
	v_mfma_f32_16x16x32_bf16 v[18:21], v[150:153], v[226:229], v[18:21]
	v_mfma_f32_16x16x32_bf16 v[10:13], v[154:157], v[222:225], 0
	v_mfma_f32_16x16x32_bf16 v[10:13], v[158:161], v[226:229], v[10:13]
	v_mfma_f32_16x16x32_bf16 v[58:61], v[162:165], v[186:189], 0
	v_mfma_f32_16x16x32_bf16 v[58:61], v[166:169], v[202:205], v[58:61]
	v_mfma_f32_16x16x32_bf16 v[54:57], v[170:173], v[186:189], 0
	v_mfma_f32_16x16x32_bf16 v[54:57], v[182:185], v[202:205], v[54:57]
	v_mfma_f32_16x16x32_bf16 v[42:45], v[162:165], v[206:209], 0
	v_mfma_f32_16x16x32_bf16 v[42:45], v[166:169], v[210:213], v[42:45]
	v_mfma_f32_16x16x32_bf16 v[38:41], v[170:173], v[206:209], 0
	v_mfma_f32_16x16x32_bf16 v[38:41], v[182:185], v[210:213], v[38:41]
	v_mfma_f32_16x16x32_bf16 v[26:29], v[162:165], v[214:217], 0
	v_mfma_f32_16x16x32_bf16 v[26:29], v[166:169], v[218:221], v[26:29]
	v_mfma_f32_16x16x32_bf16 v[22:25], v[170:173], v[214:217], 0
	v_mfma_f32_16x16x32_bf16 v[22:25], v[182:185], v[218:221], v[22:25]
	v_mfma_f32_16x16x32_bf16 v[6:9], v[162:165], v[222:225], 0
	v_mfma_f32_16x16x32_bf16 v[6:9], v[166:169], v[226:229], v[6:9]
	v_mfma_f32_16x16x32_bf16 v[2:5], v[170:173], v[222:225], 0
	v_mfma_f32_16x16x32_bf16 v[2:5], v[182:185], v[226:229], v[2:5]
	s_setprio 0
	s_barrier
	s_add_i32 s52, 0, 0x18000
	s_add_i32 s53, 0, 0x1c000
	v_add_u32_e32 v158, s52, v199
	v_add_u32_e32 v182, s53, v199
	ds_read_b128 v[134:137], v158
	ds_read_b128 v[150:153], v158 offset:1024
	ds_read_b128 v[154:157], v158 offset:2048
	ds_read_b128 v[158:161], v158 offset:3072
	ds_read_b128 v[162:165], v182
	ds_read_b128 v[166:169], v182 offset:1024
	ds_read_b128 v[170:173], v182 offset:2048
	ds_read_b128 v[182:185], v182 offset:3072
	s_add_u32 s34, s34, 0x40000
	s_addc_u32 s35, s35, 0
	s_mov_b32 m0, s41
	v_lshl_add_u64 v[234:235], s[34:35], 0, v[140:141]
	ds_read_b128 v[186:189], v201 offset:32768
	ds_read_b128 v[202:205], v201 offset:33792
	ds_read_b128 v[206:209], v201 offset:34816
	ds_read_b128 v[210:213], v201 offset:35840
	ds_read_b128 v[214:217], v201 offset:36864
	ds_read_b128 v[218:221], v201 offset:37888
	ds_read_b128 v[222:225], v201 offset:38912
	ds_read_b128 v[226:229], v201 offset:39936
	global_load_lds_dwordx4 v[234:235], off
	v_lshl_add_u64 v[234:235], s[34:35], 0, v[138:139]
	s_mov_b32 m0, s42
	s_nop 0
	global_load_lds_dwordx4 v[234:235], off
	s_waitcnt vmcnt(8)
	s_waitcnt lgkmcnt(0)
	s_barrier
	s_setprio 1
	s_waitcnt lgkmcnt(0)
	v_mfma_f32_16x16x32_bf16 v[130:133], v[134:137], v[186:189], v[130:133]
	v_mfma_f32_16x16x32_bf16 v[130:133], v[150:153], v[202:205], v[130:133]
	v_mfma_f32_16x16x32_bf16 v[126:129], v[154:157], v[186:189], v[126:129]
	v_mfma_f32_16x16x32_bf16 v[126:129], v[158:161], v[202:205], v[126:129]
	v_mfma_f32_16x16x32_bf16 v[114:117], v[134:137], v[206:209], v[114:117]
	v_mfma_f32_16x16x32_bf16 v[114:117], v[150:153], v[210:213], v[114:117]
	v_mfma_f32_16x16x32_bf16 v[110:113], v[154:157], v[206:209], v[110:113]
	v_mfma_f32_16x16x32_bf16 v[110:113], v[158:161], v[210:213], v[110:113]
	v_mfma_f32_16x16x32_bf16 v[98:101], v[134:137], v[214:217], v[98:101]
	v_mfma_f32_16x16x32_bf16 v[98:101], v[150:153], v[218:221], v[98:101]
	v_mfma_f32_16x16x32_bf16 v[94:97], v[154:157], v[214:217], v[94:97]
	v_mfma_f32_16x16x32_bf16 v[94:97], v[158:161], v[218:221], v[94:97]
	v_mfma_f32_16x16x32_bf16 v[82:85], v[134:137], v[222:225], v[82:85]
	v_mfma_f32_16x16x32_bf16 v[82:85], v[150:153], v[226:229], v[82:85]
	v_mfma_f32_16x16x32_bf16 v[78:81], v[154:157], v[222:225], v[78:81]
	v_mfma_f32_16x16x32_bf16 v[78:81], v[158:161], v[226:229], v[78:81]
	v_mfma_f32_16x16x32_bf16 v[122:125], v[162:165], v[186:189], v[122:125]
	v_mfma_f32_16x16x32_bf16 v[122:125], v[166:169], v[202:205], v[122:125]
	v_mfma_f32_16x16x32_bf16 v[118:121], v[170:173], v[186:189], v[118:121]
	v_mfma_f32_16x16x32_bf16 v[118:121], v[182:185], v[202:205], v[118:121]
	v_mfma_f32_16x16x32_bf16 v[106:109], v[162:165], v[206:209], v[106:109]
	v_mfma_f32_16x16x32_bf16 v[106:109], v[166:169], v[210:213], v[106:109]
	v_mfma_f32_16x16x32_bf16 v[102:105], v[170:173], v[206:209], v[102:105]
	v_mfma_f32_16x16x32_bf16 v[102:105], v[182:185], v[210:213], v[102:105]
	v_mfma_f32_16x16x32_bf16 v[90:93], v[162:165], v[214:217], v[90:93]
	v_mfma_f32_16x16x32_bf16 v[90:93], v[166:169], v[218:221], v[90:93]
	v_mfma_f32_16x16x32_bf16 v[86:89], v[170:173], v[214:217], v[86:89]
	v_mfma_f32_16x16x32_bf16 v[86:89], v[182:185], v[218:221], v[86:89]
	v_mfma_f32_16x16x32_bf16 v[74:77], v[162:165], v[222:225], v[74:77]
	v_mfma_f32_16x16x32_bf16 v[74:77], v[166:169], v[226:229], v[74:77]
	v_mfma_f32_16x16x32_bf16 v[70:73], v[170:173], v[222:225], v[70:73]
	v_mfma_f32_16x16x32_bf16 v[70:73], v[182:185], v[226:229], v[70:73]
	s_setprio 0
	s_barrier
	s_add_i32 s34, s52, s36
	v_lshl_add_u64 v[174:175], v[174:175], 0, s[92:93]
	s_mov_b32 m0, s34
	ds_read_b128 v[186:189], v201 offset:49152
	ds_read_b128 v[202:205], v201 offset:50176
	ds_read_b128 v[206:209], v201 offset:51200
	ds_read_b128 v[210:213], v201 offset:52224
	ds_read_b128 v[214:217], v201 offset:53248
	ds_read_b128 v[218:221], v201 offset:54272
	ds_read_b128 v[222:225], v201 offset:55296
	ds_read_b128 v[226:229], v201 offset:56320
	global_load_lds_dwordx4 v[174:175], off
	s_add_i32 m0, s34, 0x2000
	s_add_u32 s30, s30, 0x40080
	v_lshl_add_u64 v[174:175], v[190:191], 0, s[92:93]
	s_addc_u32 s31, s31, 0
	s_add_i32 s34, s53, s36
	global_load_lds_dwordx4 v[174:175], off
	v_lshl_add_u64 v[174:175], s[30:31], 0, v[0:1]
	s_mov_b32 m0, s34
	s_nop 0
	global_load_lds_dwordx4 v[174:175], off
	v_lshl_add_u64 v[174:175], s[30:31], 0, v[14:15]
	s_add_i32 m0, s34, 0x2000
	s_nop 0
	global_load_lds_dwordx4 v[174:175], off
	v_lshl_add_u64 v[174:175], v[230:231], 0, s[92:93]
	s_mov_b32 m0, s43
	s_nop 0
	global_load_lds_dwordx4 v[174:175], off
	v_lshl_add_u64 v[174:175], v[232:233], 0, s[92:93]
	s_mov_b32 m0, s44
	s_nop 0
	global_load_lds_dwordx4 v[174:175], off
	s_waitcnt vmcnt(8)
	s_waitcnt lgkmcnt(0)
	s_barrier
	s_setprio 1
	s_waitcnt lgkmcnt(0)
	v_mfma_f32_16x16x32_bf16 v[66:69], v[134:137], v[186:189], v[66:69]
	v_mfma_f32_16x16x32_bf16 v[66:69], v[150:153], v[202:205], v[66:69]
	v_mfma_f32_16x16x32_bf16 v[62:65], v[154:157], v[186:189], v[62:65]
	v_mfma_f32_16x16x32_bf16 v[62:65], v[158:161], v[202:205], v[62:65]
	v_mfma_f32_16x16x32_bf16 v[50:53], v[134:137], v[206:209], v[50:53]
	v_mfma_f32_16x16x32_bf16 v[50:53], v[150:153], v[210:213], v[50:53]
	v_mfma_f32_16x16x32_bf16 v[46:49], v[154:157], v[206:209], v[46:49]
	v_mfma_f32_16x16x32_bf16 v[46:49], v[158:161], v[210:213], v[46:49]
	v_mfma_f32_16x16x32_bf16 v[34:37], v[134:137], v[214:217], v[34:37]
	v_mfma_f32_16x16x32_bf16 v[34:37], v[150:153], v[218:221], v[34:37]
	v_mfma_f32_16x16x32_bf16 v[30:33], v[154:157], v[214:217], v[30:33]
	v_mfma_f32_16x16x32_bf16 v[30:33], v[158:161], v[218:221], v[30:33]
	v_mfma_f32_16x16x32_bf16 v[18:21], v[134:137], v[222:225], v[18:21]
	v_mfma_f32_16x16x32_bf16 v[18:21], v[150:153], v[226:229], v[18:21]
	v_mfma_f32_16x16x32_bf16 v[10:13], v[154:157], v[222:225], v[10:13]
	v_mfma_f32_16x16x32_bf16 v[10:13], v[158:161], v[226:229], v[10:13]
	v_mfma_f32_16x16x32_bf16 v[58:61], v[162:165], v[186:189], v[58:61]
	v_mfma_f32_16x16x32_bf16 v[58:61], v[166:169], v[202:205], v[58:61]
	v_mfma_f32_16x16x32_bf16 v[54:57], v[170:173], v[186:189], v[54:57]
	v_mfma_f32_16x16x32_bf16 v[54:57], v[182:185], v[202:205], v[54:57]
	v_mfma_f32_16x16x32_bf16 v[42:45], v[162:165], v[206:209], v[42:45]
	v_mfma_f32_16x16x32_bf16 v[42:45], v[166:169], v[210:213], v[42:45]
	v_mfma_f32_16x16x32_bf16 v[38:41], v[170:173], v[206:209], v[38:41]
	v_mfma_f32_16x16x32_bf16 v[38:41], v[182:185], v[210:213], v[38:41]
	v_mfma_f32_16x16x32_bf16 v[26:29], v[162:165], v[214:217], v[26:29]
	v_mfma_f32_16x16x32_bf16 v[26:29], v[166:169], v[218:221], v[26:29]
	v_mfma_f32_16x16x32_bf16 v[22:25], v[170:173], v[214:217], v[22:25]
	v_mfma_f32_16x16x32_bf16 v[22:25], v[182:185], v[218:221], v[22:25]
	v_mfma_f32_16x16x32_bf16 v[6:9], v[162:165], v[222:225], v[6:9]
	v_mfma_f32_16x16x32_bf16 v[6:9], v[166:169], v[226:229], v[6:9]
	v_mfma_f32_16x16x32_bf16 v[2:5], v[170:173], v[222:225], v[2:5]
	v_mfma_f32_16x16x32_bf16 v[2:5], v[182:185], v[226:229], v[2:5]
	s_setprio 0
	s_barrier
	s_add_i32 s51, s51, 2
	s_add_u32 s0, s0, 0x100
	s_addc_u32 s1, s1, 0
	s_add_u32 s49, s49, 0x100
	s_addc_u32 s50, s50, 0
	s_cmp_gt_u32 s51, 13
	s_cbranch_scc1 .Lpeel_exit_1
.LBB0_566:
	s_add_u32 s30, s0, 0xfffc0080
	s_addc_u32 s31, s1, -1
	s_add_i32 s52, 0, 0x10000
	s_cmp_eq_u32 s51, 12
	s_cselect_b32 s35, s3, s31
	s_cselect_b32 s34, s25, s30
	s_cselect_b32 s31, s23, s50
	s_cselect_b32 s30, s48, s49
	s_add_i32 s54, 0, 0x14000
	v_add_u32_e32 v158, s52, v199
	v_add_u32_e32 v174, s54, v199
	ds_read_b128 v[134:137], v158
	ds_read_b128 v[150:153], v158 offset:1024
	ds_read_b128 v[154:157], v158 offset:2048
	ds_read_b128 v[158:161], v158 offset:3072
	ds_read_b128 v[162:165], v174
	ds_read_b128 v[166:169], v174 offset:1024
	ds_read_b128 v[170:173], v174 offset:2048
	ds_read_b128 v[182:185], v174 offset:3072
	v_lshl_add_u64 v[174:175], s[0:1], 0, v[146:147]
	s_add_i32 m0, s39, 0xc000
	ds_read_b128 v[186:189], v201
	ds_read_b128 v[202:205], v201 offset:1024
	ds_read_b128 v[206:209], v201 offset:2048
	ds_read_b128 v[210:213], v201 offset:3072
	ds_read_b128 v[214:217], v201 offset:4096
	ds_read_b128 v[218:221], v201 offset:5120
	ds_read_b128 v[222:225], v201 offset:6144
	ds_read_b128 v[226:229], v201 offset:7168
	global_load_lds_dwordx4 v[174:175], off
	v_lshl_add_u64 v[174:175], s[0:1], 0, v[148:149]
	s_add_i32 m0, s39, 0xe000
	s_nop 0
	global_load_lds_dwordx4 v[174:175], off
	s_waitcnt vmcnt(8)
	s_waitcnt lgkmcnt(0)
	s_barrier
	s_setprio 1
	s_waitcnt lgkmcnt(0)
	v_mfma_f32_16x16x32_bf16 v[130:133], v[134:137], v[186:189], v[130:133]
	v_mfma_f32_16x16x32_bf16 v[130:133], v[150:153], v[202:205], v[130:133]
	v_mfma_f32_16x16x32_bf16 v[126:129], v[154:157], v[186:189], v[126:129]
	v_mfma_f32_16x16x32_bf16 v[126:129], v[158:161], v[202:205], v[126:129]
	v_mfma_f32_16x16x32_bf16 v[114:117], v[134:137], v[206:209], v[114:117]
	v_mfma_f32_16x16x32_bf16 v[114:117], v[150:153], v[210:213], v[114:117]
	v_mfma_f32_16x16x32_bf16 v[110:113], v[154:157], v[206:209], v[110:113]
	v_mfma_f32_16x16x32_bf16 v[110:113], v[158:161], v[210:213], v[110:113]
	v_mfma_f32_16x16x32_bf16 v[98:101], v[134:137], v[214:217], v[98:101]
	v_mfma_f32_16x16x32_bf16 v[98:101], v[150:153], v[218:221], v[98:101]
	v_mfma_f32_16x16x32_bf16 v[94:97], v[154:157], v[214:217], v[94:97]
	v_mfma_f32_16x16x32_bf16 v[94:97], v[158:161], v[218:221], v[94:97]
	v_mfma_f32_16x16x32_bf16 v[82:85], v[134:137], v[222:225], v[82:85]
	v_mfma_f32_16x16x32_bf16 v[82:85], v[150:153], v[226:229], v[82:85]
	v_mfma_f32_16x16x32_bf16 v[78:81], v[154:157], v[222:225], v[78:81]
	v_mfma_f32_16x16x32_bf16 v[78:81], v[158:161], v[226:229], v[78:81]
	v_mfma_f32_16x16x32_bf16 v[122:125], v[162:165], v[186:189], v[122:125]
	v_mfma_f32_16x16x32_bf16 v[122:125], v[166:169], v[202:205], v[122:125]
	v_mfma_f32_16x16x32_bf16 v[118:121], v[170:173], v[186:189], v[118:121]
	v_mfma_f32_16x16x32_bf16 v[118:121], v[182:185], v[202:205], v[118:121]
	v_mfma_f32_16x16x32_bf16 v[106:109], v[162:165], v[206:209], v[106:109]
	v_mfma_f32_16x16x32_bf16 v[106:109], v[166:169], v[210:213], v[106:109]
	v_mfma_f32_16x16x32_bf16 v[102:105], v[170:173], v[206:209], v[102:105]
	v_mfma_f32_16x16x32_bf16 v[102:105], v[182:185], v[210:213], v[102:105]
	v_mfma_f32_16x16x32_bf16 v[90:93], v[162:165], v[214:217], v[90:93]
	v_mfma_f32_16x16x32_bf16 v[90:93], v[166:169], v[218:221], v[90:93]
	v_mfma_f32_16x16x32_bf16 v[86:89], v[170:173], v[214:217], v[86:89]
	v_mfma_f32_16x16x32_bf16 v[86:89], v[182:185], v[218:221], v[86:89]
	v_mfma_f32_16x16x32_bf16 v[74:77], v[162:165], v[222:225], v[74:77]
	v_mfma_f32_16x16x32_bf16 v[74:77], v[166:169], v[226:229], v[74:77]
	v_mfma_f32_16x16x32_bf16 v[70:73], v[170:173], v[222:225], v[70:73]
	v_mfma_f32_16x16x32_bf16 v[70:73], v[182:185], v[226:229], v[70:73]
	s_setprio 0
	s_barrier
	s_add_i32 s52, s52, s36
	v_lshl_add_u64 v[174:175], s[30:31], 0, v[0:1]
	s_mov_b32 m0, s52
	ds_read_b128 v[186:189], v201 offset:16384
	ds_read_b128 v[202:205], v201 offset:17408
	ds_read_b128 v[206:209], v201 offset:18432
	ds_read_b128 v[210:213], v201 offset:19456
	ds_read_b128 v[214:217], v201 offset:20480
	ds_read_b128 v[218:221], v201 offset:21504
	ds_read_b128 v[222:225], v201 offset:22528
	ds_read_b128 v[226:229], v201 offset:23552
	global_load_lds_dwordx4 v[174:175], off
	s_add_i32 m0, s52, 0x2000
	s_add_u32 s52, s30, 0x40000
	v_lshl_add_u64 v[190:191], s[30:31], 0, v[14:15]
	s_addc_u32 s53, s31, 0
	s_add_i32 s54, s54, s36
	global_load_lds_dwordx4 v[190:191], off
	v_lshl_add_u64 v[230:231], s[52:53], 0, v[0:1]
	s_mov_b32 m0, s54
	v_lshl_add_u64 v[232:233], s[34:35], 0, v[138:139]
	global_load_lds_dwordx4 v[230:231], off
	v_lshl_add_u64 v[230:231], s[52:53], 0, v[14:15]
	s_add_i32 m0, s54, 0x2000
	s_nop 0
	global_load_lds_dwordx4 v[230:231], off
	v_lshl_add_u64 v[230:231], s[34:35], 0, v[140:141]
	s_mov_b32 m0, s39
	s_nop 0
	global_load_lds_dwordx4 v[230:231], off
	s_mov_b32 m0, s40
	s_nop 0
	global_load_lds_dwordx4 v[232:233], off
	s_waitcnt vmcnt(8)
	s_waitcnt lgkmcnt(0)
	s_barrier
	s_setprio 1
	s_waitcnt lgkmcnt(0)
	v_mfma_f32_16x16x32_bf16 v[66:69], v[134:137], v[186:189], v[66:69]
	v_mfma_f32_16x16x32_bf16 v[66:69], v[150:153], v[202:205], v[66:69]
	v_mfma_f32_16x16x32_bf16 v[62:65], v[154:157], v[186:189], v[62:65]
	v_mfma_f32_16x16x32_bf16 v[62:65], v[158:161], v[202:205], v[62:65]
	v_mfma_f32_16x16x32_bf16 v[50:53], v[134:137], v[206:209], v[50:53]
	v_mfma_f32_16x16x32_bf16 v[50:53], v[150:153], v[210:213], v[50:53]
	v_mfma_f32_16x16x32_bf16 v[46:49], v[154:157], v[206:209], v[46:49]
	v_mfma_f32_16x16x32_bf16 v[46:49], v[158:161], v[210:213], v[46:49]
	v_mfma_f32_16x16x32_bf16 v[34:37], v[134:137], v[214:217], v[34:37]
	v_mfma_f32_16x16x32_bf16 v[34:37], v[150:153], v[218:221], v[34:37]
	v_mfma_f32_16x16x32_bf16 v[30:33], v[154:157], v[214:217], v[30:33]
	v_mfma_f32_16x16x32_bf16 v[30:33], v[158:161], v[218:221], v[30:33]
	v_mfma_f32_16x16x32_bf16 v[18:21], v[134:137], v[222:225], v[18:21]
	v_mfma_f32_16x16x32_bf16 v[18:21], v[150:153], v[226:229], v[18:21]
	v_mfma_f32_16x16x32_bf16 v[10:13], v[154:157], v[222:225], v[10:13]
	v_mfma_f32_16x16x32_bf16 v[10:13], v[158:161], v[226:229], v[10:13]
	v_mfma_f32_16x16x32_bf16 v[58:61], v[162:165], v[186:189], v[58:61]
	v_mfma_f32_16x16x32_bf16 v[58:61], v[166:169], v[202:205], v[58:61]
	v_mfma_f32_16x16x32_bf16 v[54:57], v[170:173], v[186:189], v[54:57]
	v_mfma_f32_16x16x32_bf16 v[54:57], v[182:185], v[202:205], v[54:57]
	v_mfma_f32_16x16x32_bf16 v[42:45], v[162:165], v[206:209], v[42:45]
	v_mfma_f32_16x16x32_bf16 v[42:45], v[166:169], v[210:213], v[42:45]
	v_mfma_f32_16x16x32_bf16 v[38:41], v[170:173], v[206:209], v[38:41]
	v_mfma_f32_16x16x32_bf16 v[38:41], v[182:185], v[210:213], v[38:41]
	v_mfma_f32_16x16x32_bf16 v[26:29], v[162:165], v[214:217], v[26:29]
	v_mfma_f32_16x16x32_bf16 v[26:29], v[166:169], v[218:221], v[26:29]
	v_mfma_f32_16x16x32_bf16 v[22:25], v[170:173], v[214:217], v[22:25]
	v_mfma_f32_16x16x32_bf16 v[22:25], v[182:185], v[218:221], v[22:25]
	v_mfma_f32_16x16x32_bf16 v[6:9], v[162:165], v[222:225], v[6:9]
	v_mfma_f32_16x16x32_bf16 v[6:9], v[166:169], v[226:229], v[6:9]
	v_mfma_f32_16x16x32_bf16 v[2:5], v[170:173], v[222:225], v[2:5]
	v_mfma_f32_16x16x32_bf16 v[2:5], v[182:185], v[226:229], v[2:5]
	s_setprio 0
	s_barrier
	s_add_i32 s52, 0, 0x18000
	s_add_i32 s53, 0, 0x1c000
	v_add_u32_e32 v158, s52, v199
	v_add_u32_e32 v182, s53, v199
	ds_read_b128 v[134:137], v158
	ds_read_b128 v[150:153], v158 offset:1024
	ds_read_b128 v[154:157], v158 offset:2048
	ds_read_b128 v[158:161], v158 offset:3072
	ds_read_b128 v[162:165], v182
	ds_read_b128 v[166:169], v182 offset:1024
	ds_read_b128 v[170:173], v182 offset:2048
	ds_read_b128 v[182:185], v182 offset:3072
	s_add_u32 s34, s34, 0x40000
	s_addc_u32 s35, s35, 0
	s_mov_b32 m0, s41
	v_lshl_add_u64 v[234:235], s[34:35], 0, v[140:141]
	ds_read_b128 v[186:189], v201 offset:32768
	ds_read_b128 v[202:205], v201 offset:33792
	ds_read_b128 v[206:209], v201 offset:34816
	ds_read_b128 v[210:213], v201 offset:35840
	ds_read_b128 v[214:217], v201 offset:36864
	ds_read_b128 v[218:221], v201 offset:37888
	ds_read_b128 v[222:225], v201 offset:38912
	ds_read_b128 v[226:229], v201 offset:39936
	global_load_lds_dwordx4 v[234:235], off
	v_lshl_add_u64 v[234:235], s[34:35], 0, v[138:139]
	s_mov_b32 m0, s42
	s_nop 0
	global_load_lds_dwordx4 v[234:235], off
	s_waitcnt vmcnt(8)
	s_waitcnt lgkmcnt(0)
	s_barrier
	s_setprio 1
	s_waitcnt lgkmcnt(0)
	v_mfma_f32_16x16x32_bf16 v[130:133], v[134:137], v[186:189], v[130:133]
	v_mfma_f32_16x16x32_bf16 v[130:133], v[150:153], v[202:205], v[130:133]
	v_mfma_f32_16x16x32_bf16 v[126:129], v[154:157], v[186:189], v[126:129]
	v_mfma_f32_16x16x32_bf16 v[126:129], v[158:161], v[202:205], v[126:129]
	v_mfma_f32_16x16x32_bf16 v[114:117], v[134:137], v[206:209], v[114:117]
	v_mfma_f32_16x16x32_bf16 v[114:117], v[150:153], v[210:213], v[114:117]
	v_mfma_f32_16x16x32_bf16 v[110:113], v[154:157], v[206:209], v[110:113]
	v_mfma_f32_16x16x32_bf16 v[110:113], v[158:161], v[210:213], v[110:113]
	v_mfma_f32_16x16x32_bf16 v[98:101], v[134:137], v[214:217], v[98:101]
	v_mfma_f32_16x16x32_bf16 v[98:101], v[150:153], v[218:221], v[98:101]
	v_mfma_f32_16x16x32_bf16 v[94:97], v[154:157], v[214:217], v[94:97]
	v_mfma_f32_16x16x32_bf16 v[94:97], v[158:161], v[218:221], v[94:97]
	v_mfma_f32_16x16x32_bf16 v[82:85], v[134:137], v[222:225], v[82:85]
	v_mfma_f32_16x16x32_bf16 v[82:85], v[150:153], v[226:229], v[82:85]
	v_mfma_f32_16x16x32_bf16 v[78:81], v[154:157], v[222:225], v[78:81]
	v_mfma_f32_16x16x32_bf16 v[78:81], v[158:161], v[226:229], v[78:81]
	v_mfma_f32_16x16x32_bf16 v[122:125], v[162:165], v[186:189], v[122:125]
	v_mfma_f32_16x16x32_bf16 v[122:125], v[166:169], v[202:205], v[122:125]
	v_mfma_f32_16x16x32_bf16 v[118:121], v[170:173], v[186:189], v[118:121]
	v_mfma_f32_16x16x32_bf16 v[118:121], v[182:185], v[202:205], v[118:121]
	v_mfma_f32_16x16x32_bf16 v[106:109], v[162:165], v[206:209], v[106:109]
	v_mfma_f32_16x16x32_bf16 v[106:109], v[166:169], v[210:213], v[106:109]
	v_mfma_f32_16x16x32_bf16 v[102:105], v[170:173], v[206:209], v[102:105]
	v_mfma_f32_16x16x32_bf16 v[102:105], v[182:185], v[210:213], v[102:105]
	v_mfma_f32_16x16x32_bf16 v[90:93], v[162:165], v[214:217], v[90:93]
	v_mfma_f32_16x16x32_bf16 v[90:93], v[166:169], v[218:221], v[90:93]
	v_mfma_f32_16x16x32_bf16 v[86:89], v[170:173], v[214:217], v[86:89]
	v_mfma_f32_16x16x32_bf16 v[86:89], v[182:185], v[218:221], v[86:89]
	v_mfma_f32_16x16x32_bf16 v[74:77], v[162:165], v[222:225], v[74:77]
	v_mfma_f32_16x16x32_bf16 v[74:77], v[166:169], v[226:229], v[74:77]
	v_mfma_f32_16x16x32_bf16 v[70:73], v[170:173], v[222:225], v[70:73]
	v_mfma_f32_16x16x32_bf16 v[70:73], v[182:185], v[226:229], v[70:73]
	s_setprio 0
	s_barrier
	s_add_i32 s34, s52, s36
	v_lshl_add_u64 v[174:175], v[174:175], 0, s[92:93]
	s_mov_b32 m0, s34
	ds_read_b128 v[186:189], v201 offset:49152
	ds_read_b128 v[202:205], v201 offset:50176
	ds_read_b128 v[206:209], v201 offset:51200
	ds_read_b128 v[210:213], v201 offset:52224
	ds_read_b128 v[214:217], v201 offset:53248
	ds_read_b128 v[218:221], v201 offset:54272
	ds_read_b128 v[222:225], v201 offset:55296
	ds_read_b128 v[226:229], v201 offset:56320
	global_load_lds_dwordx4 v[174:175], off
	s_add_i32 m0, s34, 0x2000
	s_add_u32 s30, s30, 0x40080
	v_lshl_add_u64 v[174:175], v[190:191], 0, s[92:93]
	s_addc_u32 s31, s31, 0
	s_add_i32 s34, s53, s36
	global_load_lds_dwordx4 v[174:175], off
	v_lshl_add_u64 v[174:175], s[30:31], 0, v[0:1]
	s_mov_b32 m0, s34
	s_nop 0
	global_load_lds_dwordx4 v[174:175], off
	v_lshl_add_u64 v[174:175], s[30:31], 0, v[14:15]
	s_add_i32 m0, s34, 0x2000
	s_nop 0
	global_load_lds_dwordx4 v[174:175], off
	v_lshl_add_u64 v[174:175], v[230:231], 0, s[92:93]
	s_mov_b32 m0, s43
	s_nop 0
	global_load_lds_dwordx4 v[174:175], off
	v_lshl_add_u64 v[174:175], v[232:233], 0, s[92:93]
	s_mov_b32 m0, s44
	s_nop 0
	global_load_lds_dwordx4 v[174:175], off
	s_waitcnt vmcnt(8)
	s_waitcnt lgkmcnt(0)
	s_barrier
	s_setprio 1
	s_waitcnt lgkmcnt(0)
	v_mfma_f32_16x16x32_bf16 v[66:69], v[134:137], v[186:189], v[66:69]
	v_mfma_f32_16x16x32_bf16 v[66:69], v[150:153], v[202:205], v[66:69]
	v_mfma_f32_16x16x32_bf16 v[62:65], v[154:157], v[186:189], v[62:65]
	v_mfma_f32_16x16x32_bf16 v[62:65], v[158:161], v[202:205], v[62:65]
	v_mfma_f32_16x16x32_bf16 v[50:53], v[134:137], v[206:209], v[50:53]
	v_mfma_f32_16x16x32_bf16 v[50:53], v[150:153], v[210:213], v[50:53]
	v_mfma_f32_16x16x32_bf16 v[46:49], v[154:157], v[206:209], v[46:49]
	v_mfma_f32_16x16x32_bf16 v[46:49], v[158:161], v[210:213], v[46:49]
	v_mfma_f32_16x16x32_bf16 v[34:37], v[134:137], v[214:217], v[34:37]
	v_mfma_f32_16x16x32_bf16 v[34:37], v[150:153], v[218:221], v[34:37]
	v_mfma_f32_16x16x32_bf16 v[30:33], v[154:157], v[214:217], v[30:33]
	v_mfma_f32_16x16x32_bf16 v[30:33], v[158:161], v[218:221], v[30:33]
	v_mfma_f32_16x16x32_bf16 v[18:21], v[134:137], v[222:225], v[18:21]
	v_mfma_f32_16x16x32_bf16 v[18:21], v[150:153], v[226:229], v[18:21]
	v_mfma_f32_16x16x32_bf16 v[10:13], v[154:157], v[222:225], v[10:13]
	v_mfma_f32_16x16x32_bf16 v[10:13], v[158:161], v[226:229], v[10:13]
	v_mfma_f32_16x16x32_bf16 v[58:61], v[162:165], v[186:189], v[58:61]
	v_mfma_f32_16x16x32_bf16 v[58:61], v[166:169], v[202:205], v[58:61]
	v_mfma_f32_16x16x32_bf16 v[54:57], v[170:173], v[186:189], v[54:57]
	v_mfma_f32_16x16x32_bf16 v[54:57], v[182:185], v[202:205], v[54:57]
	v_mfma_f32_16x16x32_bf16 v[42:45], v[162:165], v[206:209], v[42:45]
	v_mfma_f32_16x16x32_bf16 v[42:45], v[166:169], v[210:213], v[42:45]
	v_mfma_f32_16x16x32_bf16 v[38:41], v[170:173], v[206:209], v[38:41]
	v_mfma_f32_16x16x32_bf16 v[38:41], v[182:185], v[210:213], v[38:41]
	v_mfma_f32_16x16x32_bf16 v[26:29], v[162:165], v[214:217], v[26:29]
	v_mfma_f32_16x16x32_bf16 v[26:29], v[166:169], v[218:221], v[26:29]
	v_mfma_f32_16x16x32_bf16 v[22:25], v[170:173], v[214:217], v[22:25]
	v_mfma_f32_16x16x32_bf16 v[22:25], v[182:185], v[218:221], v[22:25]
	v_mfma_f32_16x16x32_bf16 v[6:9], v[162:165], v[222:225], v[6:9]
	v_mfma_f32_16x16x32_bf16 v[6:9], v[166:169], v[226:229], v[6:9]
	v_mfma_f32_16x16x32_bf16 v[2:5], v[170:173], v[222:225], v[2:5]
	v_mfma_f32_16x16x32_bf16 v[2:5], v[182:185], v[226:229], v[2:5]
	s_setprio 0
	s_barrier
	s_add_i32 s51, s51, 2
	s_add_u32 s0, s0, 0x100
	s_addc_u32 s1, s1, 0
	s_add_u32 s49, s49, 0x100
	s_addc_u32 s50, s50, 0
	s_cmp_gt_u32 s51, 13
	s_cbranch_scc0 .LBB0_566

.LBB0_636:
	s_add_u32 s22, s22, 0x80
	s_addc_u32 s23, s23, 0
	s_add_u32 s45, s24, 0x100
	s_addc_u32 s46, s25, 0
	s_mov_b32 s24, 0
	s_add_i32 s47, s24, 2
	s_add_u32 s48, s22, 0x80
	s_addc_u32 s25, s23, 0
	s_add_i32 s50, 0, 0x10000
	s_cmp_eq_u32 s40, s24
	s_cselect_b32 s25, s7, s25
	s_cselect_b32 s24, s6, s48
	v_add_u32_e32 v135, s50, v249
	s_cselect_b32 s49, s21, s46
	s_cselect_b32 s48, s20, s45
	s_add_i32 s51, 0, 0x14000
	ds_read_b128 v[142:145], v135
	ds_read_b128 v[146:149], v135 offset:1024
	ds_read_b128 v[150:153], v135 offset:2048
	ds_read_b128 v[154:157], v135 offset:3072
	v_add_u32_e32 v135, s51, v249
	ds_read_b128 v[158:161], v135
	ds_read_b128 v[162:165], v135 offset:1024
	ds_read_b128 v[166:169], v135 offset:2048
	ds_read_b128 v[170:173], v135 offset:3072
	v_lshl_add_u64 v[174:175], s[22:23], 0, v[138:139]
	s_add_i32 m0, s31, 0xc000
	ds_read_b128 v[182:185], v251
	ds_read_b128 v[186:189], v251 offset:1024
	ds_read_b128 v[190:193], v251 offset:2048
	ds_read_b128 v[194:197], v251 offset:3072
	ds_read_b128 v[198:201], v251 offset:4096
	ds_read_b128 v[202:205], v251 offset:5120
	ds_read_b128 v[206:209], v251 offset:6144
	ds_read_b128 v[210:213], v251 offset:7168
	global_load_lds_dwordx4 v[174:175], off
	v_lshl_add_u64 v[174:175], s[22:23], 0, v[140:141]
	s_add_i32 m0, s31, 0xe000
	s_nop 0
	global_load_lds_dwordx4 v[174:175], off
	s_waitcnt vmcnt(8)
	s_waitcnt lgkmcnt(0)
	s_barrier
	s_setprio 1
	s_waitcnt lgkmcnt(0)
	v_mfma_f32_16x16x32_bf16 v[130:133], v[142:145], v[182:185], 0
	v_mfma_f32_16x16x32_bf16 v[130:133], v[146:149], v[186:189], v[130:133]
	v_mfma_f32_16x16x32_bf16 v[126:129], v[150:153], v[182:185], 0
	v_mfma_f32_16x16x32_bf16 v[126:129], v[154:157], v[186:189], v[126:129]
	v_mfma_f32_16x16x32_bf16 v[114:117], v[142:145], v[190:193], 0
	v_mfma_f32_16x16x32_bf16 v[114:117], v[146:149], v[194:197], v[114:117]
	v_mfma_f32_16x16x32_bf16 v[110:113], v[150:153], v[190:193], 0
	v_mfma_f32_16x16x32_bf16 v[110:113], v[154:157], v[194:197], v[110:113]
	v_mfma_f32_16x16x32_bf16 v[98:101], v[142:145], v[198:201], 0
	v_mfma_f32_16x16x32_bf16 v[98:101], v[146:149], v[202:205], v[98:101]
	v_mfma_f32_16x16x32_bf16 v[94:97], v[150:153], v[198:201], 0
	v_mfma_f32_16x16x32_bf16 v[94:97], v[154:157], v[202:205], v[94:97]
	v_mfma_f32_16x16x32_bf16 v[82:85], v[142:145], v[206:209], 0
	v_mfma_f32_16x16x32_bf16 v[82:85], v[146:149], v[210:213], v[82:85]
	v_mfma_f32_16x16x32_bf16 v[78:81], v[150:153], v[206:209], 0
	v_mfma_f32_16x16x32_bf16 v[78:81], v[154:157], v[210:213], v[78:81]
	v_mfma_f32_16x16x32_bf16 v[122:125], v[158:161], v[182:185], 0
	v_mfma_f32_16x16x32_bf16 v[122:125], v[162:165], v[186:189], v[122:125]
	v_mfma_f32_16x16x32_bf16 v[118:121], v[166:169], v[182:185], 0
	v_mfma_f32_16x16x32_bf16 v[118:121], v[170:173], v[186:189], v[118:121]
	v_mfma_f32_16x16x32_bf16 v[106:109], v[158:161], v[190:193], 0
	v_mfma_f32_16x16x32_bf16 v[106:109], v[162:165], v[194:197], v[106:109]
	v_mfma_f32_16x16x32_bf16 v[102:105], v[166:169], v[190:193], 0
	v_mfma_f32_16x16x32_bf16 v[102:105], v[170:173], v[194:197], v[102:105]
	v_mfma_f32_16x16x32_bf16 v[90:93], v[158:161], v[198:201], 0
	v_mfma_f32_16x16x32_bf16 v[90:93], v[162:165], v[202:205], v[90:93]
	v_mfma_f32_16x16x32_bf16 v[86:89], v[166:169], v[198:201], 0
	v_mfma_f32_16x16x32_bf16 v[86:89], v[170:173], v[202:205], v[86:89]
	v_mfma_f32_16x16x32_bf16 v[74:77], v[158:161], v[206:209], 0
	v_mfma_f32_16x16x32_bf16 v[74:77], v[162:165], v[210:213], v[74:77]
	v_mfma_f32_16x16x32_bf16 v[70:73], v[166:169], v[206:209], 0
	v_mfma_f32_16x16x32_bf16 v[70:73], v[170:173], v[210:213], v[70:73]
	s_setprio 0
	s_barrier
	s_add_i32 s50, s50, s30
	v_lshl_add_u64 v[174:175], s[48:49], 0, v[0:1]
	s_mov_b32 m0, s50
	ds_read_b128 v[182:185], v251 offset:16384
	ds_read_b128 v[186:189], v251 offset:17408
	ds_read_b128 v[190:193], v251 offset:18432
	ds_read_b128 v[194:197], v251 offset:19456
	ds_read_b128 v[198:201], v251 offset:20480
	ds_read_b128 v[202:205], v251 offset:21504
	ds_read_b128 v[206:209], v251 offset:22528
	ds_read_b128 v[210:213], v251 offset:23552
	global_load_lds_dwordx4 v[174:175], off
	s_add_i32 m0, s50, 0x2000
	v_lshl_add_u64 v[214:215], s[48:49], 0, v[14:15]
	s_add_u32 s48, s48, s10
	s_addc_u32 s49, s49, 0
	s_add_i32 s50, s51, s30
	global_load_lds_dwordx4 v[214:215], off
	v_lshl_add_u64 v[216:217], s[48:49], 0, v[0:1]
	s_mov_b32 m0, s50
	v_lshl_add_u64 v[218:219], s[48:49], 0, v[14:15]
	global_load_lds_dwordx4 v[216:217], off
	s_add_i32 m0, s50, 0x2000
	v_lshl_add_u64 v[220:221], s[24:25], 0, v[0:1]
	global_load_lds_dwordx4 v[218:219], off
	s_mov_b32 m0, s31
	v_lshl_add_u64 v[222:223], s[24:25], 0, v[14:15]
	global_load_lds_dwordx4 v[220:221], off
	s_mov_b32 m0, s34
	s_nop 0
	global_load_lds_dwordx4 v[222:223], off
	s_waitcnt vmcnt(8)
	s_waitcnt lgkmcnt(0)
	s_barrier
	s_setprio 1
	s_waitcnt lgkmcnt(0)
	v_mfma_f32_16x16x32_bf16 v[66:69], v[142:145], v[182:185], 0
	v_mfma_f32_16x16x32_bf16 v[66:69], v[146:149], v[186:189], v[66:69]
	v_mfma_f32_16x16x32_bf16 v[62:65], v[150:153], v[182:185], 0
	v_mfma_f32_16x16x32_bf16 v[62:65], v[154:157], v[186:189], v[62:65]
	v_mfma_f32_16x16x32_bf16 v[50:53], v[142:145], v[190:193], 0
	v_mfma_f32_16x16x32_bf16 v[50:53], v[146:149], v[194:197], v[50:53]
	v_mfma_f32_16x16x32_bf16 v[46:49], v[150:153], v[190:193], 0
	v_mfma_f32_16x16x32_bf16 v[46:49], v[154:157], v[194:197], v[46:49]
	v_mfma_f32_16x16x32_bf16 v[34:37], v[142:145], v[198:201], 0
	v_mfma_f32_16x16x32_bf16 v[34:37], v[146:149], v[202:205], v[34:37]
	v_mfma_f32_16x16x32_bf16 v[30:33], v[150:153], v[198:201], 0
	v_mfma_f32_16x16x32_bf16 v[30:33], v[154:157], v[202:205], v[30:33]
	v_mfma_f32_16x16x32_bf16 v[18:21], v[142:145], v[206:209], 0
	v_mfma_f32_16x16x32_bf16 v[18:21], v[146:149], v[210:213], v[18:21]
	v_mfma_f32_16x16x32_bf16 v[10:13], v[150:153], v[206:209], 0
	v_mfma_f32_16x16x32_bf16 v[10:13], v[154:157], v[210:213], v[10:13]
	v_mfma_f32_16x16x32_bf16 v[58:61], v[158:161], v[182:185], 0
	v_mfma_f32_16x16x32_bf16 v[58:61], v[162:165], v[186:189], v[58:61]
	v_mfma_f32_16x16x32_bf16 v[54:57], v[166:169], v[182:185], 0
	v_mfma_f32_16x16x32_bf16 v[54:57], v[170:173], v[186:189], v[54:57]
	v_mfma_f32_16x16x32_bf16 v[42:45], v[158:161], v[190:193], 0
	v_mfma_f32_16x16x32_bf16 v[42:45], v[162:165], v[194:197], v[42:45]
	v_mfma_f32_16x16x32_bf16 v[38:41], v[166:169], v[190:193], 0
	v_mfma_f32_16x16x32_bf16 v[38:41], v[170:173], v[194:197], v[38:41]
	v_mfma_f32_16x16x32_bf16 v[26:29], v[158:161], v[198:201], 0
	v_mfma_f32_16x16x32_bf16 v[26:29], v[162:165], v[202:205], v[26:29]
	v_mfma_f32_16x16x32_bf16 v[22:25], v[166:169], v[198:201], 0
	v_mfma_f32_16x16x32_bf16 v[22:25], v[170:173], v[202:205], v[22:25]
	v_mfma_f32_16x16x32_bf16 v[6:9], v[158:161], v[206:209], 0
	v_mfma_f32_16x16x32_bf16 v[6:9], v[162:165], v[210:213], v[6:9]
	v_mfma_f32_16x16x32_bf16 v[2:5], v[166:169], v[206:209], 0
	v_mfma_f32_16x16x32_bf16 v[2:5], v[170:173], v[210:213], v[2:5]
	s_setprio 0
	s_barrier
	s_add_i32 s48, 0, 0x18000
	v_add_u32_e32 v135, s48, v249
	s_add_i32 s49, 0, 0x1c000
	ds_read_b128 v[142:145], v135
	ds_read_b128 v[146:149], v135 offset:1024
	ds_read_b128 v[150:153], v135 offset:2048
	ds_read_b128 v[154:157], v135 offset:3072
	v_add_u32_e32 v135, s49, v249
	ds_read_b128 v[158:161], v135
	ds_read_b128 v[162:165], v135 offset:1024
	ds_read_b128 v[166:169], v135 offset:2048
	ds_read_b128 v[170:173], v135 offset:3072
	s_add_u32 s24, s24, s10
	s_addc_u32 s25, s25, 0
	s_mov_b32 m0, s35
	v_lshl_add_u64 v[224:225], s[24:25], 0, v[0:1]
	ds_read_b128 v[182:185], v251 offset:32768
	ds_read_b128 v[186:189], v251 offset:33792
	ds_read_b128 v[190:193], v251 offset:34816
	ds_read_b128 v[194:197], v251 offset:35840
	ds_read_b128 v[198:201], v251 offset:36864
	ds_read_b128 v[202:205], v251 offset:37888
	ds_read_b128 v[206:209], v251 offset:38912
	ds_read_b128 v[210:213], v251 offset:39936
	global_load_lds_dwordx4 v[224:225], off
	v_lshl_add_u64 v[224:225], s[24:25], 0, v[14:15]
	s_mov_b32 m0, s36
	s_nop 0
	global_load_lds_dwordx4 v[224:225], off
	s_waitcnt vmcnt(8)
	s_waitcnt lgkmcnt(0)
	s_barrier
	s_setprio 1
	s_waitcnt lgkmcnt(0)
	v_mfma_f32_16x16x32_bf16 v[130:133], v[142:145], v[182:185], v[130:133]
	v_mfma_f32_16x16x32_bf16 v[130:133], v[146:149], v[186:189], v[130:133]
	v_mfma_f32_16x16x32_bf16 v[126:129], v[150:153], v[182:185], v[126:129]
	v_mfma_f32_16x16x32_bf16 v[126:129], v[154:157], v[186:189], v[126:129]
	v_mfma_f32_16x16x32_bf16 v[114:117], v[142:145], v[190:193], v[114:117]
	v_mfma_f32_16x16x32_bf16 v[114:117], v[146:149], v[194:197], v[114:117]
	v_mfma_f32_16x16x32_bf16 v[110:113], v[150:153], v[190:193], v[110:113]
	v_mfma_f32_16x16x32_bf16 v[110:113], v[154:157], v[194:197], v[110:113]
	v_mfma_f32_16x16x32_bf16 v[98:101], v[142:145], v[198:201], v[98:101]
	v_mfma_f32_16x16x32_bf16 v[98:101], v[146:149], v[202:205], v[98:101]
	v_mfma_f32_16x16x32_bf16 v[94:97], v[150:153], v[198:201], v[94:97]
	v_mfma_f32_16x16x32_bf16 v[94:97], v[154:157], v[202:205], v[94:97]
	v_mfma_f32_16x16x32_bf16 v[82:85], v[142:145], v[206:209], v[82:85]
	v_mfma_f32_16x16x32_bf16 v[82:85], v[146:149], v[210:213], v[82:85]
	v_mfma_f32_16x16x32_bf16 v[78:81], v[150:153], v[206:209], v[78:81]
	v_mfma_f32_16x16x32_bf16 v[78:81], v[154:157], v[210:213], v[78:81]
	v_mfma_f32_16x16x32_bf16 v[122:125], v[158:161], v[182:185], v[122:125]
	v_mfma_f32_16x16x32_bf16 v[122:125], v[162:165], v[186:189], v[122:125]
	v_mfma_f32_16x16x32_bf16 v[118:121], v[166:169], v[182:185], v[118:121]
	v_mfma_f32_16x16x32_bf16 v[118:121], v[170:173], v[186:189], v[118:121]
	v_mfma_f32_16x16x32_bf16 v[106:109], v[158:161], v[190:193], v[106:109]
	v_mfma_f32_16x16x32_bf16 v[106:109], v[162:165], v[194:197], v[106:109]
	v_mfma_f32_16x16x32_bf16 v[102:105], v[166:169], v[190:193], v[102:105]
	v_mfma_f32_16x16x32_bf16 v[102:105], v[170:173], v[194:197], v[102:105]
	v_mfma_f32_16x16x32_bf16 v[90:93], v[158:161], v[198:201], v[90:93]
	v_mfma_f32_16x16x32_bf16 v[90:93], v[162:165], v[202:205], v[90:93]
	v_mfma_f32_16x16x32_bf16 v[86:89], v[166:169], v[198:201], v[86:89]
	v_mfma_f32_16x16x32_bf16 v[86:89], v[170:173], v[202:205], v[86:89]
	v_mfma_f32_16x16x32_bf16 v[74:77], v[158:161], v[206:209], v[74:77]
	v_mfma_f32_16x16x32_bf16 v[74:77], v[162:165], v[210:213], v[74:77]
	v_mfma_f32_16x16x32_bf16 v[70:73], v[166:169], v[206:209], v[70:73]
	v_mfma_f32_16x16x32_bf16 v[70:73], v[170:173], v[210:213], v[70:73]
	s_setprio 0
	s_barrier
	s_add_i32 s24, s48, s30
	v_lshl_add_u64 v[174:175], v[174:175], 0, s[92:93]
	s_mov_b32 m0, s24
	ds_read_b128 v[182:185], v251 offset:49152
	ds_read_b128 v[186:189], v251 offset:50176
	ds_read_b128 v[190:193], v251 offset:51200
	ds_read_b128 v[194:197], v251 offset:52224
	ds_read_b128 v[198:201], v251 offset:53248
	ds_read_b128 v[202:205], v251 offset:54272
	ds_read_b128 v[206:209], v251 offset:55296
	ds_read_b128 v[210:213], v251 offset:56320
	global_load_lds_dwordx4 v[174:175], off
	v_lshl_add_u64 v[174:175], v[214:215], 0, s[92:93]
	s_add_i32 m0, s24, 0x2000
	s_add_i32 s24, s49, s30
	global_load_lds_dwordx4 v[174:175], off
	v_lshl_add_u64 v[174:175], v[216:217], 0, s[92:93]
	s_mov_b32 m0, s24
	s_nop 0
	global_load_lds_dwordx4 v[174:175], off
	v_lshl_add_u64 v[174:175], v[218:219], 0, s[92:93]
	s_add_i32 m0, s24, 0x2000
	s_nop 0
	global_load_lds_dwordx4 v[174:175], off
	v_lshl_add_u64 v[174:175], v[220:221], 0, s[92:93]
	s_mov_b32 m0, s37
	s_nop 0
	global_load_lds_dwordx4 v[174:175], off
	v_lshl_add_u64 v[174:175], v[222:223], 0, s[92:93]
	s_mov_b32 m0, s38
	s_nop 0
	global_load_lds_dwordx4 v[174:175], off
	s_waitcnt vmcnt(8)
	s_waitcnt lgkmcnt(0)
	s_barrier
	s_setprio 1
	s_waitcnt lgkmcnt(0)
	v_mfma_f32_16x16x32_bf16 v[66:69], v[142:145], v[182:185], v[66:69]
	v_mfma_f32_16x16x32_bf16 v[66:69], v[146:149], v[186:189], v[66:69]
	v_mfma_f32_16x16x32_bf16 v[62:65], v[150:153], v[182:185], v[62:65]
	v_mfma_f32_16x16x32_bf16 v[62:65], v[154:157], v[186:189], v[62:65]
	v_mfma_f32_16x16x32_bf16 v[50:53], v[142:145], v[190:193], v[50:53]
	v_mfma_f32_16x16x32_bf16 v[50:53], v[146:149], v[194:197], v[50:53]
	v_mfma_f32_16x16x32_bf16 v[46:49], v[150:153], v[190:193], v[46:49]
	v_mfma_f32_16x16x32_bf16 v[46:49], v[154:157], v[194:197], v[46:49]
	v_mfma_f32_16x16x32_bf16 v[34:37], v[142:145], v[198:201], v[34:37]
	v_mfma_f32_16x16x32_bf16 v[34:37], v[146:149], v[202:205], v[34:37]
	v_mfma_f32_16x16x32_bf16 v[30:33], v[150:153], v[198:201], v[30:33]
	v_mfma_f32_16x16x32_bf16 v[30:33], v[154:157], v[202:205], v[30:33]
	v_mfma_f32_16x16x32_bf16 v[18:21], v[142:145], v[206:209], v[18:21]
	v_mfma_f32_16x16x32_bf16 v[18:21], v[146:149], v[210:213], v[18:21]
	v_mfma_f32_16x16x32_bf16 v[10:13], v[150:153], v[206:209], v[10:13]
	v_mfma_f32_16x16x32_bf16 v[10:13], v[154:157], v[210:213], v[10:13]
	v_mfma_f32_16x16x32_bf16 v[58:61], v[158:161], v[182:185], v[58:61]
	v_mfma_f32_16x16x32_bf16 v[58:61], v[162:165], v[186:189], v[58:61]
	v_mfma_f32_16x16x32_bf16 v[54:57], v[166:169], v[182:185], v[54:57]
	v_mfma_f32_16x16x32_bf16 v[54:57], v[170:173], v[186:189], v[54:57]
	v_mfma_f32_16x16x32_bf16 v[42:45], v[158:161], v[190:193], v[42:45]
	v_mfma_f32_16x16x32_bf16 v[42:45], v[162:165], v[194:197], v[42:45]
	v_mfma_f32_16x16x32_bf16 v[38:41], v[166:169], v[190:193], v[38:41]
	v_mfma_f32_16x16x32_bf16 v[38:41], v[170:173], v[194:197], v[38:41]
	v_mfma_f32_16x16x32_bf16 v[26:29], v[158:161], v[198:201], v[26:29]
	v_mfma_f32_16x16x32_bf16 v[26:29], v[162:165], v[202:205], v[26:29]
	v_mfma_f32_16x16x32_bf16 v[22:25], v[166:169], v[198:201], v[22:25]
	v_mfma_f32_16x16x32_bf16 v[22:25], v[170:173], v[202:205], v[22:25]
	v_mfma_f32_16x16x32_bf16 v[6:9], v[158:161], v[206:209], v[6:9]
	v_mfma_f32_16x16x32_bf16 v[6:9], v[162:165], v[210:213], v[6:9]
	v_mfma_f32_16x16x32_bf16 v[2:5], v[166:169], v[206:209], v[2:5]
	v_mfma_f32_16x16x32_bf16 v[2:5], v[170:173], v[210:213], v[2:5]
	s_setprio 0
	s_barrier
	s_add_u32 s22, s22, 0x100
	s_addc_u32 s23, s23, 0
	s_add_u32 s45, s45, 0x100
	s_addc_u32 s46, s46, 0
	s_cmp_ge_u32 s47, s39
	s_mov_b32 s24, s47
	s_cbranch_scc1 .Lpeel_exit_2
.LBB0_637:
	s_add_i32 s47, s24, 2
	s_add_u32 s48, s22, 0x80
	s_addc_u32 s25, s23, 0
	s_add_i32 s50, 0, 0x10000
	s_cmp_eq_u32 s40, s24
	s_cselect_b32 s25, s7, s25
	s_cselect_b32 s24, s6, s48
	v_add_u32_e32 v135, s50, v249
	s_cselect_b32 s49, s21, s46
	s_cselect_b32 s48, s20, s45
	s_add_i32 s51, 0, 0x14000
	ds_read_b128 v[142:145], v135
	ds_read_b128 v[146:149], v135 offset:1024
	ds_read_b128 v[150:153], v135 offset:2048
	ds_read_b128 v[154:157], v135 offset:3072
	v_add_u32_e32 v135, s51, v249
	ds_read_b128 v[158:161], v135
	ds_read_b128 v[162:165], v135 offset:1024
	ds_read_b128 v[166:169], v135 offset:2048
	ds_read_b128 v[170:173], v135 offset:3072
	v_lshl_add_u64 v[174:175], s[22:23], 0, v[138:139]
	s_add_i32 m0, s31, 0xc000
	ds_read_b128 v[182:185], v251
	ds_read_b128 v[186:189], v251 offset:1024
	ds_read_b128 v[190:193], v251 offset:2048
	ds_read_b128 v[194:197], v251 offset:3072
	ds_read_b128 v[198:201], v251 offset:4096
	ds_read_b128 v[202:205], v251 offset:5120
	ds_read_b128 v[206:209], v251 offset:6144
	ds_read_b128 v[210:213], v251 offset:7168
	global_load_lds_dwordx4 v[174:175], off
	v_lshl_add_u64 v[174:175], s[22:23], 0, v[140:141]
	s_add_i32 m0, s31, 0xe000
	s_nop 0
	global_load_lds_dwordx4 v[174:175], off
	s_waitcnt vmcnt(8)
	s_waitcnt lgkmcnt(0)
	s_barrier
	s_setprio 1
	s_waitcnt lgkmcnt(0)
	v_mfma_f32_16x16x32_bf16 v[130:133], v[142:145], v[182:185], v[130:133]
	v_mfma_f32_16x16x32_bf16 v[130:133], v[146:149], v[186:189], v[130:133]
	v_mfma_f32_16x16x32_bf16 v[126:129], v[150:153], v[182:185], v[126:129]
	v_mfma_f32_16x16x32_bf16 v[126:129], v[154:157], v[186:189], v[126:129]
	v_mfma_f32_16x16x32_bf16 v[114:117], v[142:145], v[190:193], v[114:117]
	v_mfma_f32_16x16x32_bf16 v[114:117], v[146:149], v[194:197], v[114:117]
	v_mfma_f32_16x16x32_bf16 v[110:113], v[150:153], v[190:193], v[110:113]
	v_mfma_f32_16x16x32_bf16 v[110:113], v[154:157], v[194:197], v[110:113]
	v_mfma_f32_16x16x32_bf16 v[98:101], v[142:145], v[198:201], v[98:101]
	v_mfma_f32_16x16x32_bf16 v[98:101], v[146:149], v[202:205], v[98:101]
	v_mfma_f32_16x16x32_bf16 v[94:97], v[150:153], v[198:201], v[94:97]
	v_mfma_f32_16x16x32_bf16 v[94:97], v[154:157], v[202:205], v[94:97]
	v_mfma_f32_16x16x32_bf16 v[82:85], v[142:145], v[206:209], v[82:85]
	v_mfma_f32_16x16x32_bf16 v[82:85], v[146:149], v[210:213], v[82:85]
	v_mfma_f32_16x16x32_bf16 v[78:81], v[150:153], v[206:209], v[78:81]
	v_mfma_f32_16x16x32_bf16 v[78:81], v[154:157], v[210:213], v[78:81]
	v_mfma_f32_16x16x32_bf16 v[122:125], v[158:161], v[182:185], v[122:125]
	v_mfma_f32_16x16x32_bf16 v[122:125], v[162:165], v[186:189], v[122:125]
	v_mfma_f32_16x16x32_bf16 v[118:121], v[166:169], v[182:185], v[118:121]
	v_mfma_f32_16x16x32_bf16 v[118:121], v[170:173], v[186:189], v[118:121]
	v_mfma_f32_16x16x32_bf16 v[106:109], v[158:161], v[190:193], v[106:109]
	v_mfma_f32_16x16x32_bf16 v[106:109], v[162:165], v[194:197], v[106:109]
	v_mfma_f32_16x16x32_bf16 v[102:105], v[166:169], v[190:193], v[102:105]
	v_mfma_f32_16x16x32_bf16 v[102:105], v[170:173], v[194:197], v[102:105]
	v_mfma_f32_16x16x32_bf16 v[90:93], v[158:161], v[198:201], v[90:93]
	v_mfma_f32_16x16x32_bf16 v[90:93], v[162:165], v[202:205], v[90:93]
	v_mfma_f32_16x16x32_bf16 v[86:89], v[166:169], v[198:201], v[86:89]
	v_mfma_f32_16x16x32_bf16 v[86:89], v[170:173], v[202:205], v[86:89]
	v_mfma_f32_16x16x32_bf16 v[74:77], v[158:161], v[206:209], v[74:77]
	v_mfma_f32_16x16x32_bf16 v[74:77], v[162:165], v[210:213], v[74:77]
	v_mfma_f32_16x16x32_bf16 v[70:73], v[166:169], v[206:209], v[70:73]
	v_mfma_f32_16x16x32_bf16 v[70:73], v[170:173], v[210:213], v[70:73]
	s_setprio 0
	s_barrier
	s_add_i32 s50, s50, s30
	v_lshl_add_u64 v[174:175], s[48:49], 0, v[0:1]
	s_mov_b32 m0, s50
	ds_read_b128 v[182:185], v251 offset:16384
	ds_read_b128 v[186:189], v251 offset:17408
	ds_read_b128 v[190:193], v251 offset:18432
	ds_read_b128 v[194:197], v251 offset:19456
	ds_read_b128 v[198:201], v251 offset:20480
	ds_read_b128 v[202:205], v251 offset:21504
	ds_read_b128 v[206:209], v251 offset:22528
	ds_read_b128 v[210:213], v251 offset:23552
	global_load_lds_dwordx4 v[174:175], off
	s_add_i32 m0, s50, 0x2000
	v_lshl_add_u64 v[214:215], s[48:49], 0, v[14:15]
	s_add_u32 s48, s48, s10
	s_addc_u32 s49, s49, 0
	s_add_i32 s50, s51, s30
	global_load_lds_dwordx4 v[214:215], off
	v_lshl_add_u64 v[216:217], s[48:49], 0, v[0:1]
	s_mov_b32 m0, s50
	v_lshl_add_u64 v[218:219], s[48:49], 0, v[14:15]
	global_load_lds_dwordx4 v[216:217], off
	s_add_i32 m0, s50, 0x2000
	v_lshl_add_u64 v[220:221], s[24:25], 0, v[0:1]
	global_load_lds_dwordx4 v[218:219], off
	s_mov_b32 m0, s31
	v_lshl_add_u64 v[222:223], s[24:25], 0, v[14:15]
	global_load_lds_dwordx4 v[220:221], off
	s_mov_b32 m0, s34
	s_nop 0
	global_load_lds_dwordx4 v[222:223], off
	s_waitcnt vmcnt(8)
	s_waitcnt lgkmcnt(0)
	s_barrier
	s_setprio 1
	s_waitcnt lgkmcnt(0)
	v_mfma_f32_16x16x32_bf16 v[66:69], v[142:145], v[182:185], v[66:69]
	v_mfma_f32_16x16x32_bf16 v[66:69], v[146:149], v[186:189], v[66:69]
	v_mfma_f32_16x16x32_bf16 v[62:65], v[150:153], v[182:185], v[62:65]
	v_mfma_f32_16x16x32_bf16 v[62:65], v[154:157], v[186:189], v[62:65]
	v_mfma_f32_16x16x32_bf16 v[50:53], v[142:145], v[190:193], v[50:53]
	v_mfma_f32_16x16x32_bf16 v[50:53], v[146:149], v[194:197], v[50:53]
	v_mfma_f32_16x16x32_bf16 v[46:49], v[150:153], v[190:193], v[46:49]
	v_mfma_f32_16x16x32_bf16 v[46:49], v[154:157], v[194:197], v[46:49]
	v_mfma_f32_16x16x32_bf16 v[34:37], v[142:145], v[198:201], v[34:37]
	v_mfma_f32_16x16x32_bf16 v[34:37], v[146:149], v[202:205], v[34:37]
	v_mfma_f32_16x16x32_bf16 v[30:33], v[150:153], v[198:201], v[30:33]
	v_mfma_f32_16x16x32_bf16 v[30:33], v[154:157], v[202:205], v[30:33]
	v_mfma_f32_16x16x32_bf16 v[18:21], v[142:145], v[206:209], v[18:21]
	v_mfma_f32_16x16x32_bf16 v[18:21], v[146:149], v[210:213], v[18:21]
	v_mfma_f32_16x16x32_bf16 v[10:13], v[150:153], v[206:209], v[10:13]
	v_mfma_f32_16x16x32_bf16 v[10:13], v[154:157], v[210:213], v[10:13]
	v_mfma_f32_16x16x32_bf16 v[58:61], v[158:161], v[182:185], v[58:61]
	v_mfma_f32_16x16x32_bf16 v[58:61], v[162:165], v[186:189], v[58:61]
	v_mfma_f32_16x16x32_bf16 v[54:57], v[166:169], v[182:185], v[54:57]
	v_mfma_f32_16x16x32_bf16 v[54:57], v[170:173], v[186:189], v[54:57]
	v_mfma_f32_16x16x32_bf16 v[42:45], v[158:161], v[190:193], v[42:45]
	v_mfma_f32_16x16x32_bf16 v[42:45], v[162:165], v[194:197], v[42:45]
	v_mfma_f32_16x16x32_bf16 v[38:41], v[166:169], v[190:193], v[38:41]
	v_mfma_f32_16x16x32_bf16 v[38:41], v[170:173], v[194:197], v[38:41]
	v_mfma_f32_16x16x32_bf16 v[26:29], v[158:161], v[198:201], v[26:29]
	v_mfma_f32_16x16x32_bf16 v[26:29], v[162:165], v[202:205], v[26:29]
	v_mfma_f32_16x16x32_bf16 v[22:25], v[166:169], v[198:201], v[22:25]
	v_mfma_f32_16x16x32_bf16 v[22:25], v[170:173], v[202:205], v[22:25]
	v_mfma_f32_16x16x32_bf16 v[6:9], v[158:161], v[206:209], v[6:9]
	v_mfma_f32_16x16x32_bf16 v[6:9], v[162:165], v[210:213], v[6:9]
	v_mfma_f32_16x16x32_bf16 v[2:5], v[166:169], v[206:209], v[2:5]
	v_mfma_f32_16x16x32_bf16 v[2:5], v[170:173], v[210:213], v[2:5]
	s_setprio 0
	s_barrier
	s_add_i32 s48, 0, 0x18000
	v_add_u32_e32 v135, s48, v249
	s_add_i32 s49, 0, 0x1c000
	ds_read_b128 v[142:145], v135
	ds_read_b128 v[146:149], v135 offset:1024
	ds_read_b128 v[150:153], v135 offset:2048
	ds_read_b128 v[154:157], v135 offset:3072
	v_add_u32_e32 v135, s49, v249
	ds_read_b128 v[158:161], v135
	ds_read_b128 v[162:165], v135 offset:1024
	ds_read_b128 v[166:169], v135 offset:2048
	ds_read_b128 v[170:173], v135 offset:3072
	s_add_u32 s24, s24, s10
	s_addc_u32 s25, s25, 0
	s_mov_b32 m0, s35
	v_lshl_add_u64 v[224:225], s[24:25], 0, v[0:1]
	ds_read_b128 v[182:185], v251 offset:32768
	ds_read_b128 v[186:189], v251 offset:33792
	ds_read_b128 v[190:193], v251 offset:34816
	ds_read_b128 v[194:197], v251 offset:35840
	ds_read_b128 v[198:201], v251 offset:36864
	ds_read_b128 v[202:205], v251 offset:37888
	ds_read_b128 v[206:209], v251 offset:38912
	ds_read_b128 v[210:213], v251 offset:39936
	global_load_lds_dwordx4 v[224:225], off
	v_lshl_add_u64 v[224:225], s[24:25], 0, v[14:15]
	s_mov_b32 m0, s36
	s_nop 0
	global_load_lds_dwordx4 v[224:225], off
	s_waitcnt vmcnt(8)
	s_waitcnt lgkmcnt(0)
	s_barrier
	s_setprio 1
	s_waitcnt lgkmcnt(0)
	v_mfma_f32_16x16x32_bf16 v[130:133], v[142:145], v[182:185], v[130:133]
	v_mfma_f32_16x16x32_bf16 v[130:133], v[146:149], v[186:189], v[130:133]
	v_mfma_f32_16x16x32_bf16 v[126:129], v[150:153], v[182:185], v[126:129]
	v_mfma_f32_16x16x32_bf16 v[126:129], v[154:157], v[186:189], v[126:129]
	v_mfma_f32_16x16x32_bf16 v[114:117], v[142:145], v[190:193], v[114:117]
	v_mfma_f32_16x16x32_bf16 v[114:117], v[146:149], v[194:197], v[114:117]
	v_mfma_f32_16x16x32_bf16 v[110:113], v[150:153], v[190:193], v[110:113]
	v_mfma_f32_16x16x32_bf16 v[110:113], v[154:157], v[194:197], v[110:113]
	v_mfma_f32_16x16x32_bf16 v[98:101], v[142:145], v[198:201], v[98:101]
	v_mfma_f32_16x16x32_bf16 v[98:101], v[146:149], v[202:205], v[98:101]
	v_mfma_f32_16x16x32_bf16 v[94:97], v[150:153], v[198:201], v[94:97]
	v_mfma_f32_16x16x32_bf16 v[94:97], v[154:157], v[202:205], v[94:97]
	v_mfma_f32_16x16x32_bf16 v[82:85], v[142:145], v[206:209], v[82:85]
	v_mfma_f32_16x16x32_bf16 v[82:85], v[146:149], v[210:213], v[82:85]
	v_mfma_f32_16x16x32_bf16 v[78:81], v[150:153], v[206:209], v[78:81]
	v_mfma_f32_16x16x32_bf16 v[78:81], v[154:157], v[210:213], v[78:81]
	v_mfma_f32_16x16x32_bf16 v[122:125], v[158:161], v[182:185], v[122:125]
	v_mfma_f32_16x16x32_bf16 v[122:125], v[162:165], v[186:189], v[122:125]
	v_mfma_f32_16x16x32_bf16 v[118:121], v[166:169], v[182:185], v[118:121]
	v_mfma_f32_16x16x32_bf16 v[118:121], v[170:173], v[186:189], v[118:121]
	v_mfma_f32_16x16x32_bf16 v[106:109], v[158:161], v[190:193], v[106:109]
	v_mfma_f32_16x16x32_bf16 v[106:109], v[162:165], v[194:197], v[106:109]
	v_mfma_f32_16x16x32_bf16 v[102:105], v[166:169], v[190:193], v[102:105]
	v_mfma_f32_16x16x32_bf16 v[102:105], v[170:173], v[194:197], v[102:105]
	v_mfma_f32_16x16x32_bf16 v[90:93], v[158:161], v[198:201], v[90:93]
	v_mfma_f32_16x16x32_bf16 v[90:93], v[162:165], v[202:205], v[90:93]
	v_mfma_f32_16x16x32_bf16 v[86:89], v[166:169], v[198:201], v[86:89]
	v_mfma_f32_16x16x32_bf16 v[86:89], v[170:173], v[202:205], v[86:89]
	v_mfma_f32_16x16x32_bf16 v[74:77], v[158:161], v[206:209], v[74:77]
	v_mfma_f32_16x16x32_bf16 v[74:77], v[162:165], v[210:213], v[74:77]
	v_mfma_f32_16x16x32_bf16 v[70:73], v[166:169], v[206:209], v[70:73]
	v_mfma_f32_16x16x32_bf16 v[70:73], v[170:173], v[210:213], v[70:73]
	s_setprio 0
	s_barrier
	s_add_i32 s24, s48, s30
	v_lshl_add_u64 v[174:175], v[174:175], 0, s[92:93]
	s_mov_b32 m0, s24
	ds_read_b128 v[182:185], v251 offset:49152
	ds_read_b128 v[186:189], v251 offset:50176
	ds_read_b128 v[190:193], v251 offset:51200
	ds_read_b128 v[194:197], v251 offset:52224
	ds_read_b128 v[198:201], v251 offset:53248
	ds_read_b128 v[202:205], v251 offset:54272
	ds_read_b128 v[206:209], v251 offset:55296
	ds_read_b128 v[210:213], v251 offset:56320
	global_load_lds_dwordx4 v[174:175], off
	v_lshl_add_u64 v[174:175], v[214:215], 0, s[92:93]
	s_add_i32 m0, s24, 0x2000
	s_add_i32 s24, s49, s30
	global_load_lds_dwordx4 v[174:175], off
	v_lshl_add_u64 v[174:175], v[216:217], 0, s[92:93]
	s_mov_b32 m0, s24
	s_nop 0
	global_load_lds_dwordx4 v[174:175], off
	v_lshl_add_u64 v[174:175], v[218:219], 0, s[92:93]
	s_add_i32 m0, s24, 0x2000
	s_nop 0
	global_load_lds_dwordx4 v[174:175], off
	v_lshl_add_u64 v[174:175], v[220:221], 0, s[92:93]
	s_mov_b32 m0, s37
	s_nop 0
	global_load_lds_dwordx4 v[174:175], off
	v_lshl_add_u64 v[174:175], v[222:223], 0, s[92:93]
	s_mov_b32 m0, s38
	s_nop 0
	global_load_lds_dwordx4 v[174:175], off
	s_waitcnt vmcnt(8)
	s_waitcnt lgkmcnt(0)
	s_barrier
	s_setprio 1
	s_waitcnt lgkmcnt(0)
	v_mfma_f32_16x16x32_bf16 v[66:69], v[142:145], v[182:185], v[66:69]
	v_mfma_f32_16x16x32_bf16 v[66:69], v[146:149], v[186:189], v[66:69]
	v_mfma_f32_16x16x32_bf16 v[62:65], v[150:153], v[182:185], v[62:65]
	v_mfma_f32_16x16x32_bf16 v[62:65], v[154:157], v[186:189], v[62:65]
	v_mfma_f32_16x16x32_bf16 v[50:53], v[142:145], v[190:193], v[50:53]
	v_mfma_f32_16x16x32_bf16 v[50:53], v[146:149], v[194:197], v[50:53]
	v_mfma_f32_16x16x32_bf16 v[46:49], v[150:153], v[190:193], v[46:49]
	v_mfma_f32_16x16x32_bf16 v[46:49], v[154:157], v[194:197], v[46:49]
	v_mfma_f32_16x16x32_bf16 v[34:37], v[142:145], v[198:201], v[34:37]
	v_mfma_f32_16x16x32_bf16 v[34:37], v[146:149], v[202:205], v[34:37]
	v_mfma_f32_16x16x32_bf16 v[30:33], v[150:153], v[198:201], v[30:33]
	v_mfma_f32_16x16x32_bf16 v[30:33], v[154:157], v[202:205], v[30:33]
	v_mfma_f32_16x16x32_bf16 v[18:21], v[142:145], v[206:209], v[18:21]
	v_mfma_f32_16x16x32_bf16 v[18:21], v[146:149], v[210:213], v[18:21]
	v_mfma_f32_16x16x32_bf16 v[10:13], v[150:153], v[206:209], v[10:13]
	v_mfma_f32_16x16x32_bf16 v[10:13], v[154:157], v[210:213], v[10:13]
	v_mfma_f32_16x16x32_bf16 v[58:61], v[158:161], v[182:185], v[58:61]
	v_mfma_f32_16x16x32_bf16 v[58:61], v[162:165], v[186:189], v[58:61]
	v_mfma_f32_16x16x32_bf16 v[54:57], v[166:169], v[182:185], v[54:57]
	v_mfma_f32_16x16x32_bf16 v[54:57], v[170:173], v[186:189], v[54:57]
	v_mfma_f32_16x16x32_bf16 v[42:45], v[158:161], v[190:193], v[42:45]
	v_mfma_f32_16x16x32_bf16 v[42:45], v[162:165], v[194:197], v[42:45]
	v_mfma_f32_16x16x32_bf16 v[38:41], v[166:169], v[190:193], v[38:41]
	v_mfma_f32_16x16x32_bf16 v[38:41], v[170:173], v[194:197], v[38:41]
	v_mfma_f32_16x16x32_bf16 v[26:29], v[158:161], v[198:201], v[26:29]
	v_mfma_f32_16x16x32_bf16 v[26:29], v[162:165], v[202:205], v[26:29]
	v_mfma_f32_16x16x32_bf16 v[22:25], v[166:169], v[198:201], v[22:25]
	v_mfma_f32_16x16x32_bf16 v[22:25], v[170:173], v[202:205], v[22:25]
	v_mfma_f32_16x16x32_bf16 v[6:9], v[158:161], v[206:209], v[6:9]
	v_mfma_f32_16x16x32_bf16 v[6:9], v[162:165], v[210:213], v[6:9]
	v_mfma_f32_16x16x32_bf16 v[2:5], v[166:169], v[206:209], v[2:5]
	v_mfma_f32_16x16x32_bf16 v[2:5], v[170:173], v[210:213], v[2:5]
	s_setprio 0
	s_barrier
	s_add_u32 s22, s22, 0x100
	s_addc_u32 s23, s23, 0
	s_add_u32 s45, s45, 0x100
	s_addc_u32 s46, s46, 0
	s_cmp_ge_u32 s47, s39
	s_mov_b32 s24, s47
	s_cbranch_scc0 .LBB0_637

.Lg3_join_w1_pl3:
	s_waitcnt lgkmcnt(0)
	s_barrier
	s_setprio 1
	s_waitcnt lgkmcnt(0)
	v_mfma_f32_16x16x32_bf16 v[130:133], v[134:137], v[194:197], 0
	v_mfma_f32_16x16x32_bf16 v[130:133], v[148:151], v[198:201], v[130:133]
	v_mfma_f32_16x16x32_bf16 v[122:125], v[152:155], v[194:197], 0
	v_mfma_f32_16x16x32_bf16 v[122:125], v[156:159], v[198:201], v[122:125]
	v_mfma_f32_16x16x32_bf16 v[114:117], v[134:137], v[202:205], 0
	v_mfma_f32_16x16x32_bf16 v[114:117], v[148:151], v[206:209], v[114:117]
	v_mfma_f32_16x16x32_bf16 v[106:109], v[152:155], v[202:205], 0
	v_mfma_f32_16x16x32_bf16 v[106:109], v[156:159], v[206:209], v[106:109]
	v_mfma_f32_16x16x32_bf16 v[98:101], v[134:137], v[210:213], 0
	v_mfma_f32_16x16x32_bf16 v[98:101], v[148:151], v[214:217], v[98:101]
	v_mfma_f32_16x16x32_bf16 v[90:93], v[152:155], v[210:213], 0
	v_mfma_f32_16x16x32_bf16 v[90:93], v[156:159], v[214:217], v[90:93]
	v_mfma_f32_16x16x32_bf16 v[82:85], v[134:137], v[218:221], 0
	v_mfma_f32_16x16x32_bf16 v[82:85], v[148:151], v[222:225], v[82:85]
	v_mfma_f32_16x16x32_bf16 v[74:77], v[152:155], v[218:221], 0
	v_mfma_f32_16x16x32_bf16 v[74:77], v[156:159], v[222:225], v[74:77]
	v_mfma_f32_16x16x32_bf16 v[126:129], v[160:163], v[194:197], 0
	v_mfma_f32_16x16x32_bf16 v[126:129], v[182:185], v[198:201], v[126:129]
	v_mfma_f32_16x16x32_bf16 v[118:121], v[186:189], v[194:197], 0
	v_mfma_f32_16x16x32_bf16 v[118:121], v[190:193], v[198:201], v[118:121]
	v_mfma_f32_16x16x32_bf16 v[110:113], v[160:163], v[202:205], 0
	v_mfma_f32_16x16x32_bf16 v[110:113], v[182:185], v[206:209], v[110:113]
	v_mfma_f32_16x16x32_bf16 v[102:105], v[186:189], v[202:205], 0
	v_mfma_f32_16x16x32_bf16 v[102:105], v[190:193], v[206:209], v[102:105]
	v_mfma_f32_16x16x32_bf16 v[94:97], v[160:163], v[210:213], 0
	v_mfma_f32_16x16x32_bf16 v[94:97], v[182:185], v[214:217], v[94:97]
	v_mfma_f32_16x16x32_bf16 v[86:89], v[186:189], v[210:213], 0
	v_mfma_f32_16x16x32_bf16 v[86:89], v[190:193], v[214:217], v[86:89]
	v_mfma_f32_16x16x32_bf16 v[78:81], v[160:163], v[218:221], 0
	v_mfma_f32_16x16x32_bf16 v[78:81], v[182:185], v[222:225], v[78:81]
	v_mfma_f32_16x16x32_bf16 v[70:73], v[186:189], v[218:221], 0
	v_mfma_f32_16x16x32_bf16 v[70:73], v[190:193], v[222:225], v[70:73]
	s_setprio 0
	s_barrier
	s_add_i32 s41, s41, s13
	v_lshl_add_u64 v[226:227], s[20:21], 0, v[0:1]
	s_mov_b32 m0, s41
	ds_read_b128 v[194:197], v175 offset:16384
	ds_read_b128 v[198:201], v175 offset:17408
	ds_read_b128 v[202:205], v175 offset:18432
	ds_read_b128 v[206:209], v175 offset:19456
	ds_read_b128 v[210:213], v175 offset:20480
	ds_read_b128 v[214:217], v175 offset:21504
	ds_read_b128 v[218:221], v175 offset:22528
	ds_read_b128 v[222:225], v175 offset:23552
	global_load_lds_dwordx4 v[226:227], off
	s_add_i32 m0, s41, 0x2000
	s_add_u32 s42, s20, 0x40000
	v_lshl_add_u64 v[228:229], s[20:21], 0, v[14:15]
	s_addc_u32 s43, s21, 0
	s_add_i32 s41, s44, s13
	global_load_lds_dwordx4 v[228:229], off
	v_lshl_add_u64 v[230:231], s[42:43], 0, v[0:1]
	s_mov_b32 m0, s41
	v_lshl_add_u64 v[232:233], s[22:23], 0, v[138:139]
	global_load_lds_dwordx4 v[230:231], off
	v_lshl_add_u64 v[230:231], s[42:43], 0, v[14:15]
	s_add_i32 m0, s41, 0x2000
	s_nop 0
	global_load_lds_dwordx4 v[230:231], off
	v_lshl_add_u64 v[230:231], s[22:23], 0, v[140:141]
	s_mov_b32 m0, s26
	s_nop 0
	global_load_lds_dwordx4 v[230:231], off
	s_mov_b32 m0, s27
	s_nop 0
	global_load_lds_dwordx4 v[232:233], off
	s_cmp_eq_i32 s40, -2
	s_cselect_b32 s98, s2, 0
	s_cmp_lg_u32 s98, 0
	s_cbranch_scc1 .Lg3_relax_w2_pl3
	s_waitcnt vmcnt(8)
	s_branch .Lg3_join_w2_pl3

.Lg3_join_w2_pl3:
	s_waitcnt lgkmcnt(0)
	s_barrier
	s_setprio 1
	s_waitcnt lgkmcnt(0)
	v_mfma_f32_16x16x32_bf16 v[66:69], v[134:137], v[194:197], 0
	v_mfma_f32_16x16x32_bf16 v[66:69], v[148:151], v[198:201], v[66:69]
	v_mfma_f32_16x16x32_bf16 v[58:61], v[152:155], v[194:197], 0
	v_mfma_f32_16x16x32_bf16 v[58:61], v[156:159], v[198:201], v[58:61]
	v_mfma_f32_16x16x32_bf16 v[50:53], v[134:137], v[202:205], 0
	v_mfma_f32_16x16x32_bf16 v[50:53], v[148:151], v[206:209], v[50:53]
	v_mfma_f32_16x16x32_bf16 v[42:45], v[152:155], v[202:205], 0
	v_mfma_f32_16x16x32_bf16 v[42:45], v[156:159], v[206:209], v[42:45]
	v_mfma_f32_16x16x32_bf16 v[34:37], v[134:137], v[210:213], 0
	v_mfma_f32_16x16x32_bf16 v[34:37], v[148:151], v[214:217], v[34:37]
	v_mfma_f32_16x16x32_bf16 v[26:29], v[152:155], v[210:213], 0
	v_mfma_f32_16x16x32_bf16 v[26:29], v[156:159], v[214:217], v[26:29]
	v_mfma_f32_16x16x32_bf16 v[18:21], v[134:137], v[218:221], 0
	v_mfma_f32_16x16x32_bf16 v[18:21], v[148:151], v[222:225], v[18:21]
	v_mfma_f32_16x16x32_bf16 v[6:9], v[152:155], v[218:221], 0
	v_mfma_f32_16x16x32_bf16 v[6:9], v[156:159], v[222:225], v[6:9]
	v_mfma_f32_16x16x32_bf16 v[62:65], v[160:163], v[194:197], 0
	v_mfma_f32_16x16x32_bf16 v[62:65], v[182:185], v[198:201], v[62:65]
	v_mfma_f32_16x16x32_bf16 v[54:57], v[186:189], v[194:197], 0
	v_mfma_f32_16x16x32_bf16 v[54:57], v[190:193], v[198:201], v[54:57]
	v_mfma_f32_16x16x32_bf16 v[46:49], v[160:163], v[202:205], 0
	v_mfma_f32_16x16x32_bf16 v[46:49], v[182:185], v[206:209], v[46:49]
	v_mfma_f32_16x16x32_bf16 v[38:41], v[186:189], v[202:205], 0
	v_mfma_f32_16x16x32_bf16 v[38:41], v[190:193], v[206:209], v[38:41]
	v_mfma_f32_16x16x32_bf16 v[30:33], v[160:163], v[210:213], 0
	v_mfma_f32_16x16x32_bf16 v[30:33], v[182:185], v[214:217], v[30:33]
	v_mfma_f32_16x16x32_bf16 v[22:25], v[186:189], v[210:213], 0
	v_mfma_f32_16x16x32_bf16 v[22:25], v[190:193], v[214:217], v[22:25]
	v_mfma_f32_16x16x32_bf16 v[10:13], v[160:163], v[218:221], 0
	v_mfma_f32_16x16x32_bf16 v[10:13], v[182:185], v[222:225], v[10:13]
	v_mfma_f32_16x16x32_bf16 v[2:5], v[186:189], v[218:221], 0
	v_mfma_f32_16x16x32_bf16 v[2:5], v[190:193], v[222:225], v[2:5]
	s_setprio 0
	s_barrier
	s_add_i32 s41, 0, 0x18000
	s_add_i32 s42, 0, 0x1c000
	v_add_u32_e32 v156, s41, v171
	v_add_u32_e32 v164, s42, v171
	ds_read_b128 v[134:137], v156
	ds_read_b128 v[148:151], v156 offset:1024
	ds_read_b128 v[152:155], v156 offset:2048
	ds_read_b128 v[156:159], v156 offset:3072
	ds_read_b128 v[160:163], v164
	ds_read_b128 v[182:185], v164 offset:1024
	ds_read_b128 v[186:189], v164 offset:2048
	ds_read_b128 v[190:193], v164 offset:3072
	s_add_u32 s22, s22, 0x40000
	s_addc_u32 s23, s23, 0
	s_mov_b32 m0, s28
	v_lshl_add_u64 v[234:235], s[22:23], 0, v[140:141]
	ds_read_b128 v[194:197], v175 offset:32768
	ds_read_b128 v[198:201], v175 offset:33792
	ds_read_b128 v[202:205], v175 offset:34816
	ds_read_b128 v[206:209], v175 offset:35840
	ds_read_b128 v[210:213], v175 offset:36864
	ds_read_b128 v[214:217], v175 offset:37888
	ds_read_b128 v[218:221], v175 offset:38912
	ds_read_b128 v[222:225], v175 offset:39936
	global_load_lds_dwordx4 v[234:235], off
	v_lshl_add_u64 v[234:235], s[22:23], 0, v[138:139]
	s_mov_b32 m0, s29
	s_nop 0
	global_load_lds_dwordx4 v[234:235], off
	s_waitcnt vmcnt(8)
	s_waitcnt lgkmcnt(0)
	s_barrier
	s_setprio 1
	s_waitcnt lgkmcnt(0)
	v_mfma_f32_16x16x32_bf16 v[130:133], v[134:137], v[194:197], v[130:133]
	v_mfma_f32_16x16x32_bf16 v[130:133], v[148:151], v[198:201], v[130:133]
	v_mfma_f32_16x16x32_bf16 v[122:125], v[152:155], v[194:197], v[122:125]
	v_mfma_f32_16x16x32_bf16 v[122:125], v[156:159], v[198:201], v[122:125]
	v_mfma_f32_16x16x32_bf16 v[114:117], v[134:137], v[202:205], v[114:117]
	v_mfma_f32_16x16x32_bf16 v[114:117], v[148:151], v[206:209], v[114:117]
	v_mfma_f32_16x16x32_bf16 v[106:109], v[152:155], v[202:205], v[106:109]
	v_mfma_f32_16x16x32_bf16 v[106:109], v[156:159], v[206:209], v[106:109]
	v_mfma_f32_16x16x32_bf16 v[98:101], v[134:137], v[210:213], v[98:101]
	v_mfma_f32_16x16x32_bf16 v[98:101], v[148:151], v[214:217], v[98:101]
	v_mfma_f32_16x16x32_bf16 v[90:93], v[152:155], v[210:213], v[90:93]
	v_mfma_f32_16x16x32_bf16 v[90:93], v[156:159], v[214:217], v[90:93]
	v_mfma_f32_16x16x32_bf16 v[82:85], v[134:137], v[218:221], v[82:85]
	v_mfma_f32_16x16x32_bf16 v[82:85], v[148:151], v[222:225], v[82:85]
	v_mfma_f32_16x16x32_bf16 v[74:77], v[152:155], v[218:221], v[74:77]
	v_mfma_f32_16x16x32_bf16 v[74:77], v[156:159], v[222:225], v[74:77]
	v_mfma_f32_16x16x32_bf16 v[126:129], v[160:163], v[194:197], v[126:129]
	v_mfma_f32_16x16x32_bf16 v[126:129], v[182:185], v[198:201], v[126:129]
	v_mfma_f32_16x16x32_bf16 v[118:121], v[186:189], v[194:197], v[118:121]
	v_mfma_f32_16x16x32_bf16 v[118:121], v[190:193], v[198:201], v[118:121]
	v_mfma_f32_16x16x32_bf16 v[110:113], v[160:163], v[202:205], v[110:113]
	v_mfma_f32_16x16x32_bf16 v[110:113], v[182:185], v[206:209], v[110:113]
	v_mfma_f32_16x16x32_bf16 v[102:105], v[186:189], v[202:205], v[102:105]
	v_mfma_f32_16x16x32_bf16 v[102:105], v[190:193], v[206:209], v[102:105]
	v_mfma_f32_16x16x32_bf16 v[94:97], v[160:163], v[210:213], v[94:97]
	v_mfma_f32_16x16x32_bf16 v[94:97], v[182:185], v[214:217], v[94:97]
	v_mfma_f32_16x16x32_bf16 v[86:89], v[186:189], v[210:213], v[86:89]
	v_mfma_f32_16x16x32_bf16 v[86:89], v[190:193], v[214:217], v[86:89]
	v_mfma_f32_16x16x32_bf16 v[78:81], v[160:163], v[218:221], v[78:81]
	v_mfma_f32_16x16x32_bf16 v[78:81], v[182:185], v[222:225], v[78:81]
	v_mfma_f32_16x16x32_bf16 v[70:73], v[186:189], v[218:221], v[70:73]
	v_mfma_f32_16x16x32_bf16 v[70:73], v[190:193], v[222:225], v[70:73]
	s_setprio 0
	s_barrier
	s_add_i32 s22, s41, s13
	v_lshl_add_u64 v[226:227], v[226:227], 0, s[92:93]
	s_mov_b32 m0, s22
	ds_read_b128 v[194:197], v175 offset:49152
	ds_read_b128 v[198:201], v175 offset:50176
	ds_read_b128 v[202:205], v175 offset:51200
	ds_read_b128 v[206:209], v175 offset:52224
	ds_read_b128 v[210:213], v175 offset:53248
	ds_read_b128 v[214:217], v175 offset:54272
	ds_read_b128 v[218:221], v175 offset:55296
	ds_read_b128 v[222:225], v175 offset:56320
	global_load_lds_dwordx4 v[226:227], off
	s_add_i32 m0, s22, 0x2000
	s_add_u32 s20, s20, 0x40080
	v_lshl_add_u64 v[226:227], v[228:229], 0, s[92:93]
	s_addc_u32 s21, s21, 0
	s_add_i32 s22, s42, s13
	global_load_lds_dwordx4 v[226:227], off
	v_lshl_add_u64 v[226:227], s[20:21], 0, v[0:1]
	s_mov_b32 m0, s22
	s_nop 0
	global_load_lds_dwordx4 v[226:227], off
	v_lshl_add_u64 v[226:227], s[20:21], 0, v[14:15]
	s_add_i32 m0, s22, 0x2000
	s_nop 0
	global_load_lds_dwordx4 v[226:227], off
	v_lshl_add_u64 v[226:227], v[230:231], 0, s[92:93]
	s_mov_b32 m0, s30
	s_nop 0
	global_load_lds_dwordx4 v[226:227], off
	v_lshl_add_u64 v[226:227], v[232:233], 0, s[92:93]
	s_mov_b32 m0, s31
	s_nop 0
	global_load_lds_dwordx4 v[226:227], off
	s_waitcnt vmcnt(8)
	s_waitcnt lgkmcnt(0)
	s_barrier
	s_setprio 1
	s_waitcnt lgkmcnt(0)
	v_mfma_f32_16x16x32_bf16 v[66:69], v[134:137], v[194:197], v[66:69]
	v_mfma_f32_16x16x32_bf16 v[66:69], v[148:151], v[198:201], v[66:69]
	v_mfma_f32_16x16x32_bf16 v[58:61], v[152:155], v[194:197], v[58:61]
	v_mfma_f32_16x16x32_bf16 v[58:61], v[156:159], v[198:201], v[58:61]
	v_mfma_f32_16x16x32_bf16 v[50:53], v[134:137], v[202:205], v[50:53]
	v_mfma_f32_16x16x32_bf16 v[50:53], v[148:151], v[206:209], v[50:53]
	v_mfma_f32_16x16x32_bf16 v[42:45], v[152:155], v[202:205], v[42:45]
	v_mfma_f32_16x16x32_bf16 v[42:45], v[156:159], v[206:209], v[42:45]
	v_mfma_f32_16x16x32_bf16 v[34:37], v[134:137], v[210:213], v[34:37]
	v_mfma_f32_16x16x32_bf16 v[34:37], v[148:151], v[214:217], v[34:37]
	v_mfma_f32_16x16x32_bf16 v[26:29], v[152:155], v[210:213], v[26:29]
	v_mfma_f32_16x16x32_bf16 v[26:29], v[156:159], v[214:217], v[26:29]
	v_mfma_f32_16x16x32_bf16 v[18:21], v[134:137], v[218:221], v[18:21]
	v_mfma_f32_16x16x32_bf16 v[18:21], v[148:151], v[222:225], v[18:21]
	v_mfma_f32_16x16x32_bf16 v[6:9], v[152:155], v[218:221], v[6:9]
	v_mfma_f32_16x16x32_bf16 v[6:9], v[156:159], v[222:225], v[6:9]
	v_mfma_f32_16x16x32_bf16 v[62:65], v[160:163], v[194:197], v[62:65]
	v_mfma_f32_16x16x32_bf16 v[62:65], v[182:185], v[198:201], v[62:65]
	v_mfma_f32_16x16x32_bf16 v[54:57], v[186:189], v[194:197], v[54:57]
	v_mfma_f32_16x16x32_bf16 v[54:57], v[190:193], v[198:201], v[54:57]
	v_mfma_f32_16x16x32_bf16 v[46:49], v[160:163], v[202:205], v[46:49]
	v_mfma_f32_16x16x32_bf16 v[46:49], v[182:185], v[206:209], v[46:49]
	v_mfma_f32_16x16x32_bf16 v[38:41], v[186:189], v[202:205], v[38:41]
	v_mfma_f32_16x16x32_bf16 v[38:41], v[190:193], v[206:209], v[38:41]
	v_mfma_f32_16x16x32_bf16 v[30:33], v[160:163], v[210:213], v[30:33]
	v_mfma_f32_16x16x32_bf16 v[30:33], v[182:185], v[214:217], v[30:33]
	v_mfma_f32_16x16x32_bf16 v[22:25], v[186:189], v[210:213], v[22:25]
	v_mfma_f32_16x16x32_bf16 v[22:25], v[190:193], v[214:217], v[22:25]
	v_mfma_f32_16x16x32_bf16 v[10:13], v[160:163], v[218:221], v[10:13]
	v_mfma_f32_16x16x32_bf16 v[10:13], v[182:185], v[222:225], v[10:13]
	v_mfma_f32_16x16x32_bf16 v[2:5], v[186:189], v[218:221], v[2:5]
	v_mfma_f32_16x16x32_bf16 v[2:5], v[190:193], v[222:225], v[2:5]
	s_setprio 0
	s_barrier
	s_add_i32 s40, s40, 2
	s_add_u32 s4, s4, 0x100
	s_addc_u32 s5, s5, 0
	s_add_u32 s38, s38, 0x100
	s_addc_u32 s39, s39, 0
	s_cmp_gt_u32 s40, 13
	s_cbranch_scc1 .Lpeel_exit_3

.Lg3_join_w1:
	s_waitcnt lgkmcnt(0)
	s_barrier
	s_setprio 1
	s_waitcnt lgkmcnt(0)
	v_mfma_f32_16x16x32_bf16 v[130:133], v[134:137], v[194:197], v[130:133]
	v_mfma_f32_16x16x32_bf16 v[130:133], v[148:151], v[198:201], v[130:133]
	v_mfma_f32_16x16x32_bf16 v[122:125], v[152:155], v[194:197], v[122:125]
	v_mfma_f32_16x16x32_bf16 v[122:125], v[156:159], v[198:201], v[122:125]
	v_mfma_f32_16x16x32_bf16 v[114:117], v[134:137], v[202:205], v[114:117]
	v_mfma_f32_16x16x32_bf16 v[114:117], v[148:151], v[206:209], v[114:117]
	v_mfma_f32_16x16x32_bf16 v[106:109], v[152:155], v[202:205], v[106:109]
	v_mfma_f32_16x16x32_bf16 v[106:109], v[156:159], v[206:209], v[106:109]
	v_mfma_f32_16x16x32_bf16 v[98:101], v[134:137], v[210:213], v[98:101]
	v_mfma_f32_16x16x32_bf16 v[98:101], v[148:151], v[214:217], v[98:101]
	v_mfma_f32_16x16x32_bf16 v[90:93], v[152:155], v[210:213], v[90:93]
	v_mfma_f32_16x16x32_bf16 v[90:93], v[156:159], v[214:217], v[90:93]
	v_mfma_f32_16x16x32_bf16 v[82:85], v[134:137], v[218:221], v[82:85]
	v_mfma_f32_16x16x32_bf16 v[82:85], v[148:151], v[222:225], v[82:85]
	v_mfma_f32_16x16x32_bf16 v[74:77], v[152:155], v[218:221], v[74:77]
	v_mfma_f32_16x16x32_bf16 v[74:77], v[156:159], v[222:225], v[74:77]
	v_mfma_f32_16x16x32_bf16 v[126:129], v[160:163], v[194:197], v[126:129]
	v_mfma_f32_16x16x32_bf16 v[126:129], v[182:185], v[198:201], v[126:129]
	v_mfma_f32_16x16x32_bf16 v[118:121], v[186:189], v[194:197], v[118:121]
	v_mfma_f32_16x16x32_bf16 v[118:121], v[190:193], v[198:201], v[118:121]
	v_mfma_f32_16x16x32_bf16 v[110:113], v[160:163], v[202:205], v[110:113]
	v_mfma_f32_16x16x32_bf16 v[110:113], v[182:185], v[206:209], v[110:113]
	v_mfma_f32_16x16x32_bf16 v[102:105], v[186:189], v[202:205], v[102:105]
	v_mfma_f32_16x16x32_bf16 v[102:105], v[190:193], v[206:209], v[102:105]
	v_mfma_f32_16x16x32_bf16 v[94:97], v[160:163], v[210:213], v[94:97]
	v_mfma_f32_16x16x32_bf16 v[94:97], v[182:185], v[214:217], v[94:97]
	v_mfma_f32_16x16x32_bf16 v[86:89], v[186:189], v[210:213], v[86:89]
	v_mfma_f32_16x16x32_bf16 v[86:89], v[190:193], v[214:217], v[86:89]
	v_mfma_f32_16x16x32_bf16 v[78:81], v[160:163], v[218:221], v[78:81]
	v_mfma_f32_16x16x32_bf16 v[78:81], v[182:185], v[222:225], v[78:81]
	v_mfma_f32_16x16x32_bf16 v[70:73], v[186:189], v[218:221], v[70:73]
	v_mfma_f32_16x16x32_bf16 v[70:73], v[190:193], v[222:225], v[70:73]
	s_setprio 0
	s_barrier
	s_add_i32 s41, s41, s13
	v_lshl_add_u64 v[226:227], s[20:21], 0, v[0:1]
	s_mov_b32 m0, s41
	ds_read_b128 v[194:197], v175 offset:16384
	ds_read_b128 v[198:201], v175 offset:17408
	ds_read_b128 v[202:205], v175 offset:18432
	ds_read_b128 v[206:209], v175 offset:19456
	ds_read_b128 v[210:213], v175 offset:20480
	ds_read_b128 v[214:217], v175 offset:21504
	ds_read_b128 v[218:221], v175 offset:22528
	ds_read_b128 v[222:225], v175 offset:23552
	global_load_lds_dwordx4 v[226:227], off
	s_add_i32 m0, s41, 0x2000
	s_add_u32 s42, s20, 0x40000
	v_lshl_add_u64 v[228:229], s[20:21], 0, v[14:15]
	s_addc_u32 s43, s21, 0
	s_add_i32 s41, s44, s13
	global_load_lds_dwordx4 v[228:229], off
	v_lshl_add_u64 v[230:231], s[42:43], 0, v[0:1]
	s_mov_b32 m0, s41
	v_lshl_add_u64 v[232:233], s[22:23], 0, v[138:139]
	global_load_lds_dwordx4 v[230:231], off
	v_lshl_add_u64 v[230:231], s[42:43], 0, v[14:15]
	s_add_i32 m0, s41, 0x2000
	s_nop 0
	global_load_lds_dwordx4 v[230:231], off
	v_lshl_add_u64 v[230:231], s[22:23], 0, v[140:141]
	s_mov_b32 m0, s26
	s_nop 0
	global_load_lds_dwordx4 v[230:231], off
	s_mov_b32 m0, s27
	s_nop 0
	global_load_lds_dwordx4 v[232:233], off
	s_cmp_eq_i32 s40, -2
	s_cselect_b32 s98, s2, 0
	s_cmp_lg_u32 s98, 0
	s_cbranch_scc1 .Lg3_relax_w2
	s_waitcnt vmcnt(8)
	s_branch .Lg3_join_w2

.Lg3_join_w2:
	s_waitcnt lgkmcnt(0)
	s_barrier
	s_setprio 1
	s_waitcnt lgkmcnt(0)
	v_mfma_f32_16x16x32_bf16 v[66:69], v[134:137], v[194:197], v[66:69]
	v_mfma_f32_16x16x32_bf16 v[66:69], v[148:151], v[198:201], v[66:69]
	v_mfma_f32_16x16x32_bf16 v[58:61], v[152:155], v[194:197], v[58:61]
	v_mfma_f32_16x16x32_bf16 v[58:61], v[156:159], v[198:201], v[58:61]
	v_mfma_f32_16x16x32_bf16 v[50:53], v[134:137], v[202:205], v[50:53]
	v_mfma_f32_16x16x32_bf16 v[50:53], v[148:151], v[206:209], v[50:53]
	v_mfma_f32_16x16x32_bf16 v[42:45], v[152:155], v[202:205], v[42:45]
	v_mfma_f32_16x16x32_bf16 v[42:45], v[156:159], v[206:209], v[42:45]
	v_mfma_f32_16x16x32_bf16 v[34:37], v[134:137], v[210:213], v[34:37]
	v_mfma_f32_16x16x32_bf16 v[34:37], v[148:151], v[214:217], v[34:37]
	v_mfma_f32_16x16x32_bf16 v[26:29], v[152:155], v[210:213], v[26:29]
	v_mfma_f32_16x16x32_bf16 v[26:29], v[156:159], v[214:217], v[26:29]
	v_mfma_f32_16x16x32_bf16 v[18:21], v[134:137], v[218:221], v[18:21]
	v_mfma_f32_16x16x32_bf16 v[18:21], v[148:151], v[222:225], v[18:21]
	v_mfma_f32_16x16x32_bf16 v[6:9], v[152:155], v[218:221], v[6:9]
	v_mfma_f32_16x16x32_bf16 v[6:9], v[156:159], v[222:225], v[6:9]
	v_mfma_f32_16x16x32_bf16 v[62:65], v[160:163], v[194:197], v[62:65]
	v_mfma_f32_16x16x32_bf16 v[62:65], v[182:185], v[198:201], v[62:65]
	v_mfma_f32_16x16x32_bf16 v[54:57], v[186:189], v[194:197], v[54:57]
	v_mfma_f32_16x16x32_bf16 v[54:57], v[190:193], v[198:201], v[54:57]
	v_mfma_f32_16x16x32_bf16 v[46:49], v[160:163], v[202:205], v[46:49]
	v_mfma_f32_16x16x32_bf16 v[46:49], v[182:185], v[206:209], v[46:49]
	v_mfma_f32_16x16x32_bf16 v[38:41], v[186:189], v[202:205], v[38:41]
	v_mfma_f32_16x16x32_bf16 v[38:41], v[190:193], v[206:209], v[38:41]
	v_mfma_f32_16x16x32_bf16 v[30:33], v[160:163], v[210:213], v[30:33]
	v_mfma_f32_16x16x32_bf16 v[30:33], v[182:185], v[214:217], v[30:33]
	v_mfma_f32_16x16x32_bf16 v[22:25], v[186:189], v[210:213], v[22:25]
	v_mfma_f32_16x16x32_bf16 v[22:25], v[190:193], v[214:217], v[22:25]
	v_mfma_f32_16x16x32_bf16 v[10:13], v[160:163], v[218:221], v[10:13]
	v_mfma_f32_16x16x32_bf16 v[10:13], v[182:185], v[222:225], v[10:13]
	v_mfma_f32_16x16x32_bf16 v[2:5], v[186:189], v[218:221], v[2:5]
	v_mfma_f32_16x16x32_bf16 v[2:5], v[190:193], v[222:225], v[2:5]
	s_setprio 0
	s_barrier
	s_add_i32 s41, 0, 0x18000
	s_add_i32 s42, 0, 0x1c000
	v_add_u32_e32 v156, s41, v171
	v_add_u32_e32 v164, s42, v171
	ds_read_b128 v[134:137], v156
	ds_read_b128 v[148:151], v156 offset:1024
	ds_read_b128 v[152:155], v156 offset:2048
	ds_read_b128 v[156:159], v156 offset:3072
	ds_read_b128 v[160:163], v164
	ds_read_b128 v[182:185], v164 offset:1024
	ds_read_b128 v[186:189], v164 offset:2048
	ds_read_b128 v[190:193], v164 offset:3072
	s_add_u32 s22, s22, 0x40000
	s_addc_u32 s23, s23, 0
	s_mov_b32 m0, s28
	v_lshl_add_u64 v[234:235], s[22:23], 0, v[140:141]
	ds_read_b128 v[194:197], v175 offset:32768
	ds_read_b128 v[198:201], v175 offset:33792
	ds_read_b128 v[202:205], v175 offset:34816
	ds_read_b128 v[206:209], v175 offset:35840
	ds_read_b128 v[210:213], v175 offset:36864
	ds_read_b128 v[214:217], v175 offset:37888
	ds_read_b128 v[218:221], v175 offset:38912
	ds_read_b128 v[222:225], v175 offset:39936
	global_load_lds_dwordx4 v[234:235], off
	v_lshl_add_u64 v[234:235], s[22:23], 0, v[138:139]
	s_mov_b32 m0, s29
	s_nop 0
	global_load_lds_dwordx4 v[234:235], off
	s_waitcnt vmcnt(8)
	s_waitcnt lgkmcnt(0)
	s_barrier
	s_setprio 1
	s_waitcnt lgkmcnt(0)
	v_mfma_f32_16x16x32_bf16 v[130:133], v[134:137], v[194:197], v[130:133]
	v_mfma_f32_16x16x32_bf16 v[130:133], v[148:151], v[198:201], v[130:133]
	v_mfma_f32_16x16x32_bf16 v[122:125], v[152:155], v[194:197], v[122:125]
	v_mfma_f32_16x16x32_bf16 v[122:125], v[156:159], v[198:201], v[122:125]
	v_mfma_f32_16x16x32_bf16 v[114:117], v[134:137], v[202:205], v[114:117]
	v_mfma_f32_16x16x32_bf16 v[114:117], v[148:151], v[206:209], v[114:117]
	v_mfma_f32_16x16x32_bf16 v[106:109], v[152:155], v[202:205], v[106:109]
	v_mfma_f32_16x16x32_bf16 v[106:109], v[156:159], v[206:209], v[106:109]
	v_mfma_f32_16x16x32_bf16 v[98:101], v[134:137], v[210:213], v[98:101]
	v_mfma_f32_16x16x32_bf16 v[98:101], v[148:151], v[214:217], v[98:101]
	v_mfma_f32_16x16x32_bf16 v[90:93], v[152:155], v[210:213], v[90:93]
	v_mfma_f32_16x16x32_bf16 v[90:93], v[156:159], v[214:217], v[90:93]
	v_mfma_f32_16x16x32_bf16 v[82:85], v[134:137], v[218:221], v[82:85]
	v_mfma_f32_16x16x32_bf16 v[82:85], v[148:151], v[222:225], v[82:85]
	v_mfma_f32_16x16x32_bf16 v[74:77], v[152:155], v[218:221], v[74:77]
	v_mfma_f32_16x16x32_bf16 v[74:77], v[156:159], v[222:225], v[74:77]
	v_mfma_f32_16x16x32_bf16 v[126:129], v[160:163], v[194:197], v[126:129]
	v_mfma_f32_16x16x32_bf16 v[126:129], v[182:185], v[198:201], v[126:129]
	v_mfma_f32_16x16x32_bf16 v[118:121], v[186:189], v[194:197], v[118:121]
	v_mfma_f32_16x16x32_bf16 v[118:121], v[190:193], v[198:201], v[118:121]
	v_mfma_f32_16x16x32_bf16 v[110:113], v[160:163], v[202:205], v[110:113]
	v_mfma_f32_16x16x32_bf16 v[110:113], v[182:185], v[206:209], v[110:113]
	v_mfma_f32_16x16x32_bf16 v[102:105], v[186:189], v[202:205], v[102:105]
	v_mfma_f32_16x16x32_bf16 v[102:105], v[190:193], v[206:209], v[102:105]
	v_mfma_f32_16x16x32_bf16 v[94:97], v[160:163], v[210:213], v[94:97]
	v_mfma_f32_16x16x32_bf16 v[94:97], v[182:185], v[214:217], v[94:97]
	v_mfma_f32_16x16x32_bf16 v[86:89], v[186:189], v[210:213], v[86:89]
	v_mfma_f32_16x16x32_bf16 v[86:89], v[190:193], v[214:217], v[86:89]
	v_mfma_f32_16x16x32_bf16 v[78:81], v[160:163], v[218:221], v[78:81]
	v_mfma_f32_16x16x32_bf16 v[78:81], v[182:185], v[222:225], v[78:81]
	v_mfma_f32_16x16x32_bf16 v[70:73], v[186:189], v[218:221], v[70:73]
	v_mfma_f32_16x16x32_bf16 v[70:73], v[190:193], v[222:225], v[70:73]
	s_setprio 0
	s_barrier
	s_add_i32 s22, s41, s13
	v_lshl_add_u64 v[226:227], v[226:227], 0, s[92:93]
	s_mov_b32 m0, s22
	ds_read_b128 v[194:197], v175 offset:49152
	ds_read_b128 v[198:201], v175 offset:50176
	ds_read_b128 v[202:205], v175 offset:51200
	ds_read_b128 v[206:209], v175 offset:52224
	ds_read_b128 v[210:213], v175 offset:53248
	ds_read_b128 v[214:217], v175 offset:54272
	ds_read_b128 v[218:221], v175 offset:55296
	ds_read_b128 v[222:225], v175 offset:56320
	global_load_lds_dwordx4 v[226:227], off
	s_add_i32 m0, s22, 0x2000
	s_add_u32 s20, s20, 0x40080
	v_lshl_add_u64 v[226:227], v[228:229], 0, s[92:93]
	s_addc_u32 s21, s21, 0
	s_add_i32 s22, s42, s13
	global_load_lds_dwordx4 v[226:227], off
	v_lshl_add_u64 v[226:227], s[20:21], 0, v[0:1]
	s_mov_b32 m0, s22
	s_nop 0
	global_load_lds_dwordx4 v[226:227], off
	v_lshl_add_u64 v[226:227], s[20:21], 0, v[14:15]
	s_add_i32 m0, s22, 0x2000
	s_nop 0
	global_load_lds_dwordx4 v[226:227], off
	v_lshl_add_u64 v[226:227], v[230:231], 0, s[92:93]
	s_mov_b32 m0, s30
	s_nop 0
	global_load_lds_dwordx4 v[226:227], off
	v_lshl_add_u64 v[226:227], v[232:233], 0, s[92:93]
	s_mov_b32 m0, s31
	s_nop 0
	global_load_lds_dwordx4 v[226:227], off
	s_waitcnt vmcnt(8)
	s_waitcnt lgkmcnt(0)
	s_barrier
	s_setprio 1
	s_waitcnt lgkmcnt(0)
	v_mfma_f32_16x16x32_bf16 v[66:69], v[134:137], v[194:197], v[66:69]
	v_mfma_f32_16x16x32_bf16 v[66:69], v[148:151], v[198:201], v[66:69]
	v_mfma_f32_16x16x32_bf16 v[58:61], v[152:155], v[194:197], v[58:61]
	v_mfma_f32_16x16x32_bf16 v[58:61], v[156:159], v[198:201], v[58:61]
	v_mfma_f32_16x16x32_bf16 v[50:53], v[134:137], v[202:205], v[50:53]
	v_mfma_f32_16x16x32_bf16 v[50:53], v[148:151], v[206:209], v[50:53]
	v_mfma_f32_16x16x32_bf16 v[42:45], v[152:155], v[202:205], v[42:45]
	v_mfma_f32_16x16x32_bf16 v[42:45], v[156:159], v[206:209], v[42:45]
	v_mfma_f32_16x16x32_bf16 v[34:37], v[134:137], v[210:213], v[34:37]
	v_mfma_f32_16x16x32_bf16 v[34:37], v[148:151], v[214:217], v[34:37]
	v_mfma_f32_16x16x32_bf16 v[26:29], v[152:155], v[210:213], v[26:29]
	v_mfma_f32_16x16x32_bf16 v[26:29], v[156:159], v[214:217], v[26:29]
	v_mfma_f32_16x16x32_bf16 v[18:21], v[134:137], v[218:221], v[18:21]
	v_mfma_f32_16x16x32_bf16 v[18:21], v[148:151], v[222:225], v[18:21]
	v_mfma_f32_16x16x32_bf16 v[6:9], v[152:155], v[218:221], v[6:9]
	v_mfma_f32_16x16x32_bf16 v[6:9], v[156:159], v[222:225], v[6:9]
	v_mfma_f32_16x16x32_bf16 v[62:65], v[160:163], v[194:197], v[62:65]
	v_mfma_f32_16x16x32_bf16 v[62:65], v[182:185], v[198:201], v[62:65]
	v_mfma_f32_16x16x32_bf16 v[54:57], v[186:189], v[194:197], v[54:57]
	v_mfma_f32_16x16x32_bf16 v[54:57], v[190:193], v[198:201], v[54:57]
	v_mfma_f32_16x16x32_bf16 v[46:49], v[160:163], v[202:205], v[46:49]
	v_mfma_f32_16x16x32_bf16 v[46:49], v[182:185], v[206:209], v[46:49]
	v_mfma_f32_16x16x32_bf16 v[38:41], v[186:189], v[202:205], v[38:41]
	v_mfma_f32_16x16x32_bf16 v[38:41], v[190:193], v[206:209], v[38:41]
	v_mfma_f32_16x16x32_bf16 v[30:33], v[160:163], v[210:213], v[30:33]
	v_mfma_f32_16x16x32_bf16 v[30:33], v[182:185], v[214:217], v[30:33]
	v_mfma_f32_16x16x32_bf16 v[22:25], v[186:189], v[210:213], v[22:25]
	v_mfma_f32_16x16x32_bf16 v[22:25], v[190:193], v[214:217], v[22:25]
	v_mfma_f32_16x16x32_bf16 v[10:13], v[160:163], v[218:221], v[10:13]
	v_mfma_f32_16x16x32_bf16 v[10:13], v[182:185], v[222:225], v[10:13]
	v_mfma_f32_16x16x32_bf16 v[2:5], v[186:189], v[218:221], v[2:5]
	v_mfma_f32_16x16x32_bf16 v[2:5], v[190:193], v[222:225], v[2:5]
	s_setprio 0
	s_barrier
	s_add_i32 s40, s40, 2
	s_add_u32 s4, s4, 0x100
	s_addc_u32 s5, s5, 0
	s_add_u32 s38, s38, 0x100
	s_addc_u32 s39, s39, 0
	s_cmp_gt_u32 s40, 13
	s_cbranch_scc0 .LBB0_893
